# speedup vs baseline: 1.0261x; 1.0048x over previous
; DEVI float row16_sum(float v) {
;   v += dppf<0xB1, 0xF>(0.f, v); v += dppf<0x4E, 0xF>(0.f, v); v += dppf<0x141, 0xF>(0.f, v); v += dppf<0x140, 0xF>(0.f, v); return v;
; }
; DEVI float row16_max(float v) {
;   v = fmaxf(v, dppf<0xB1, 0xF>(v, v)); v = fmaxf(v, dppf<0x4E, 0xF>(v, v)); v = fmaxf(v, dppf<0x141, 0xF>(v, v)); v = fmaxf(v, dppf<0x140, 0xF>(v, v)); return v;
; }
; DEVI float wave_sum(float v) {
;   v = row16_sum(v);
;   v += dppf<0x142, 0xA>(0.f, v); v += dppf<0x143, 0xC>(0.f, v);
;   return __int_as_float(__builtin_amdgcn_readlane(__float_as_int(v), 63));
; }
; DEVI float shflx(float v, int lane, int m) { return __int_as_float(__builtin_amdgcn_ds_bpermute((lane ^ m) << 2, __float_as_int(v))); }
; DEVI float shfll(float v, int src) { return __int_as_float(__builtin_amdgcn_ds_bpermute(src << 2, __float_as_int(v))); }
; DEVI float half32_sum(float v, int lane) {
;   v = row16_sum(v); v += shflx(v, lane, 16); return v;
;   DEVI void operator()(f32x16* acc, int mrow, int pn, int r32, int hi, char* slice) const {
;     ...
;     if (pn < 10) {
;       const float* gain = (pn < 8 ? p->in[I_AQG] : p->in[I_AKG]) + j_attn * 128;
;       float rstd[16];
; #pragma unroll
;       for (int r = 0; r < 16; ++r) {
;         float ss = 0.f;
; #pragma unroll
;         for (int j = 0; j < 4; ++j) ss += acc[j][r] * acc[j][r];
;         ss = half32_sum(ss, hi * 32 + r32);
;         rstd[r] = rsqrtf(ss * (1.f / 128.f) + EPS);
.LBB0_2824:
	s_mul_hi_i32 s0, s52, 0x2aaaaaab
	s_lshr_b32 s1, s0, 31
	s_ashr_i32 s51, s0, 1
	s_add_i32 s51, s51, s1
	s_lshl_b32 s0, s51, s25
	s_add_i32 s1, s0, s24
	s_mul_i32 s0, s51, -12
	s_add_i32 s0, s52, s0
	v_lshl_add_u32 v198, s1, 8, v167
	s_cmp_lt_i32 s0, 10
	s_movk_i32 s1, 0x7fff
	v_cmp_gt_i32_e64 s[44:45], s79, v198
	s_cselect_b64 s[16:17], -1, 0
	s_cmp_gt_i32 s0, 9
	v_cmp_lt_i32_e64 s[42:43], s1, v198
	s_cbranch_scc1 .LBB0_2955
	v_mov_b32_e32 v136, v50
	v_mov_b32_e32 v137, v34
	v_mov_b32_e32 v140, v51
	v_mov_b32_e32 v141, v35
	v_pk_mul_f32 v[136:137], v[136:137], v[136:137]
	v_mov_b32_e32 v138, v18
	v_mov_b32_e32 v139, v2
	v_pk_mul_f32 v[140:141], v[140:141], v[140:141]
	v_mov_b32_e32 v142, v19
	v_mov_b32_e32 v143, v3
	v_pk_mul_f32 v[138:139], v[138:139], v[138:139]
	v_pk_mul_f32 v[142:143], v[142:143], v[142:143]
	v_mov_b32_e32 v144, v140
	v_mov_b32_e32 v145, v136
	v_mov_b32_e32 v136, v141
	v_pk_add_f32 v[136:137], v[144:145], v[136:137]
	v_mov_b32_e32 v140, v142
	v_mov_b32_e32 v141, v138
	v_pk_add_f32 v[136:137], v[136:137], v[140:141]
	v_mov_b32_e32 v138, v143
	v_pk_add_f32 v[136:137], v[136:137], v[138:139]
	v_mov_b32_e32 v139, v1
	v_mov_b32_e32 v138, v1
	s_brev_b32 s22, 60
	v_mov_b32_dpp v139, v137 quad_perm:[1,0,3,2] row_mask:0xf bank_mask:0xf
	v_mov_b32_dpp v138, v136 quad_perm:[1,0,3,2] row_mask:0xf bank_mask:0xf
	v_pk_add_f32 v[136:137], v[136:137], v[138:139]
	v_mov_b32_e32 v139, v1
	v_mov_b32_e32 v138, v1
	v_mov_b32_e32 v140, v53
	v_mov_b32_dpp v139, v137 quad_perm:[2,3,0,1] row_mask:0xf bank_mask:0xf
	v_mov_b32_dpp v138, v136 quad_perm:[2,3,0,1] row_mask:0xf bank_mask:0xf
	v_pk_add_f32 v[136:137], v[136:137], v[138:139]
	v_mov_b32_e32 v139, v1
	v_mov_b32_e32 v138, v1
	v_mov_b32_e32 v141, v37
	v_mov_b32_dpp v139, v137 row_half_mirror row_mask:0xf bank_mask:0xf
	v_mov_b32_dpp v138, v136 row_half_mirror row_mask:0xf bank_mask:0xf
	v_pk_add_f32 v[136:137], v[136:137], v[138:139]
	v_mov_b32_e32 v139, v1
	v_mov_b32_e32 v138, v1
	v_pk_mul_f32 v[140:141], v[140:141], v[140:141]
	v_mov_b32_dpp v139, v137 row_mirror row_mask:0xf bank_mask:0xf
	v_mov_b32_dpp v138, v136 row_mirror row_mask:0xf bank_mask:0xf
	v_pk_add_f32 v[136:137], v[136:137], v[138:139]
	ds_bpermute_b32 v139, v168, v137
	ds_bpermute_b32 v138, v168, v136
	v_mov_b32_e32 v142, v21
	v_mov_b32_e32 v143, v5
	v_pk_mul_f32 v[142:143], v[142:143], v[142:143]
	v_mov_b32_e32 v146, v140
	s_waitcnt lgkmcnt(0)
	v_pk_add_f32 v[136:137], v[136:137], v[138:139]
	v_mov_b32_e32 v138, v20
	v_pk_fma_f32 v[144:145], v[136:137], s[22:23], v[178:179] op_sel_hi:[1,0,0]
	v_mov_b32_e32 v139, v4
	v_mul_f32_e32 v136, 0x4b800000, v145
	v_cmp_gt_f32_e64 s[46:47], s26, v145
	v_pk_mul_f32 v[138:139], v[138:139], v[138:139]
	v_mov_b32_e32 v140, v142
	v_cndmask_b32_e64 v136, v145, v136, s[46:47]
	v_rsq_f32_e32 v136, v136
	v_mov_b32_e32 v142, v23
	v_readlane_b32 s2, v255, 8
	v_readlane_b32 s3, v255, 9
	v_mul_f32_e32 v137, 0x45800000, v136
	v_cndmask_b32_e64 v199, v136, v137, s[46:47]
	v_mov_b32_e32 v136, v52
	v_mov_b32_e32 v137, v36
	v_pk_mul_f32 v[136:137], v[136:137], v[136:137]
	s_load_dwordx16 s[56:71], s[2:3], 0x40
	v_mov_b32_e32 v147, v136
	v_mov_b32_e32 v136, v141
	v_pk_add_f32 v[136:137], v[146:147], v[136:137]
	v_mov_b32_e32 v141, v138
	v_pk_add_f32 v[136:137], v[136:137], v[140:141]
	v_mov_b32_e32 v138, v143
	v_pk_add_f32 v[136:137], v[136:137], v[138:139]
	v_mov_b32_e32 v139, v1
	v_mov_b32_e32 v138, v1
	v_mov_b32_e32 v140, v55
	v_mov_b32_dpp v139, v137 quad_perm:[1,0,3,2] row_mask:0xf bank_mask:0xf
	v_mov_b32_dpp v138, v136 quad_perm:[1,0,3,2] row_mask:0xf bank_mask:0xf
	v_pk_add_f32 v[136:137], v[136:137], v[138:139]
	v_mov_b32_e32 v139, v1
	v_mov_b32_e32 v138, v1
	v_mov_b32_e32 v141, v39
	v_mov_b32_dpp v139, v137 quad_perm:[2,3,0,1] row_mask:0xf bank_mask:0xf
	v_mov_b32_dpp v138, v136 quad_perm:[2,3,0,1] row_mask:0xf bank_mask:0xf
	v_pk_add_f32 v[136:137], v[136:137], v[138:139]
	v_mov_b32_e32 v139, v1
	v_mov_b32_e32 v138, v1
	v_pk_mul_f32 v[140:141], v[140:141], v[140:141]
	v_mov_b32_dpp v139, v137 row_half_mirror row_mask:0xf bank_mask:0xf
	v_mov_b32_dpp v138, v136 row_half_mirror row_mask:0xf bank_mask:0xf
	v_pk_add_f32 v[136:137], v[136:137], v[138:139]
	v_mov_b32_e32 v139, v1
	v_mov_b32_e32 v138, v1
	v_mov_b32_e32 v143, v7
	v_mov_b32_dpp v139, v137 row_mirror row_mask:0xf bank_mask:0xf
	v_mov_b32_dpp v138, v136 row_mirror row_mask:0xf bank_mask:0xf
	v_pk_add_f32 v[162:163], v[136:137], v[138:139]
	v_mov_b32_e32 v136, v54
	v_mov_b32_e32 v137, v38
	v_pk_mul_f32 v[136:137], v[136:137], v[136:137]
	v_mov_b32_e32 v138, v22
	v_mov_b32_e32 v139, v6
	v_pk_mul_f32 v[138:139], v[138:139], v[138:139]
	v_pk_mul_f32 v[142:143], v[142:143], v[142:143]
	v_mov_b32_e32 v146, v140
	v_mov_b32_e32 v147, v136
	v_mov_b32_e32 v136, v141
	v_pk_add_f32 v[136:137], v[146:147], v[136:137]
	v_mov_b32_e32 v140, v142
	v_mov_b32_e32 v141, v138
	v_pk_add_f32 v[136:137], v[136:137], v[140:141]
	v_mov_b32_e32 v138, v143
	v_pk_add_f32 v[136:137], v[136:137], v[138:139]
	v_mov_b32_e32 v139, v1
	v_mov_b32_e32 v138, v1
	v_mov_b32_e32 v140, v57
	v_mov_b32_dpp v139, v137 quad_perm:[1,0,3,2] row_mask:0xf bank_mask:0xf
	v_mov_b32_dpp v138, v136 quad_perm:[1,0,3,2] row_mask:0xf bank_mask:0xf
	v_pk_add_f32 v[136:137], v[136:137], v[138:139]
	v_mov_b32_e32 v139, v1
	v_mov_b32_e32 v138, v1
	v_mov_b32_e32 v141, v41
	v_mov_b32_dpp v139, v137 quad_perm:[2,3,0,1] row_mask:0xf bank_mask:0xf
	v_mov_b32_dpp v138, v136 quad_perm:[2,3,0,1] row_mask:0xf bank_mask:0xf
	v_pk_add_f32 v[136:137], v[136:137], v[138:139]
	v_mov_b32_e32 v139, v1
	v_mov_b32_e32 v138, v1
	v_pk_mul_f32 v[140:141], v[140:141], v[140:141]
; DEVI float row16_sum(float v) {
;   v += dppf<0xB1, 0xF>(0.f, v); v += dppf<0x4E, 0xF>(0.f, v); v += dppf<0x141, 0xF>(0.f, v); v += dppf<0x140, 0xF>(0.f, v); return v;
; }
;   DEVI void operator()(f32x16* acc, int mrow, int pn, int r32, int hi, char* slice) const {
;     ...
;       for (int r = 0; r < 16; ++r) {
;         float ss = 0.f;
; #pragma unroll
;         for (int j = 0; j < 4; ++j) ss += acc[j][r] * acc[j][r];
;         ss = half32_sum(ss, hi * 32 + r32);
;         rstd[r] = rsqrtf(ss * (1.f / 128.f) + EPS);
	v_mov_b32_dpp v139, v137 row_half_mirror row_mask:0xf bank_mask:0xf
	v_mov_b32_dpp v138, v136 row_half_mirror row_mask:0xf bank_mask:0xf
	v_pk_add_f32 v[136:137], v[136:137], v[138:139]
	v_mov_b32_e32 v139, v1
	v_mov_b32_e32 v138, v1
	v_mov_b32_e32 v142, v25
	v_mov_b32_dpp v139, v137 row_mirror row_mask:0xf bank_mask:0xf
	v_mov_b32_dpp v138, v136 row_mirror row_mask:0xf bank_mask:0xf
	v_pk_add_f32 v[158:159], v[136:137], v[138:139]
	v_mov_b32_e32 v136, v56
	v_mov_b32_e32 v137, v40
	v_pk_mul_f32 v[136:137], v[136:137], v[136:137]
	v_mov_b32_e32 v138, v24
	v_mov_b32_e32 v139, v8
	v_mov_b32_e32 v143, v9
	v_pk_mul_f32 v[138:139], v[138:139], v[138:139]
	v_pk_mul_f32 v[142:143], v[142:143], v[142:143]
	v_mov_b32_e32 v146, v140
	v_mov_b32_e32 v147, v136
	v_mov_b32_e32 v136, v141
	v_pk_add_f32 v[136:137], v[146:147], v[136:137]
	v_mov_b32_e32 v140, v142
	v_mov_b32_e32 v141, v138
	v_pk_add_f32 v[136:137], v[136:137], v[140:141]
	v_mov_b32_e32 v138, v143
	v_pk_add_f32 v[136:137], v[136:137], v[138:139]
	v_mov_b32_e32 v139, v1
	v_mov_b32_e32 v138, v1
	v_mov_b32_e32 v140, v59
	v_mov_b32_dpp v139, v137 quad_perm:[1,0,3,2] row_mask:0xf bank_mask:0xf
	v_mov_b32_dpp v138, v136 quad_perm:[1,0,3,2] row_mask:0xf bank_mask:0xf
	v_pk_add_f32 v[136:137], v[136:137], v[138:139]
	v_mov_b32_e32 v139, v1
	v_mov_b32_e32 v138, v1
	v_mov_b32_e32 v141, v43
	v_mov_b32_dpp v139, v137 quad_perm:[2,3,0,1] row_mask:0xf bank_mask:0xf
	v_mov_b32_dpp v138, v136 quad_perm:[2,3,0,1] row_mask:0xf bank_mask:0xf
	v_pk_add_f32 v[136:137], v[136:137], v[138:139]
	v_mov_b32_e32 v139, v1
	v_mov_b32_e32 v138, v1
	v_pk_mul_f32 v[140:141], v[140:141], v[140:141]
	v_mov_b32_dpp v139, v137 row_half_mirror row_mask:0xf bank_mask:0xf
	v_mov_b32_dpp v138, v136 row_half_mirror row_mask:0xf bank_mask:0xf
	v_pk_add_f32 v[136:137], v[136:137], v[138:139]
	v_mov_b32_e32 v139, v1
	v_mov_b32_e32 v138, v1
	v_mov_b32_e32 v142, v27
	v_mov_b32_dpp v139, v137 row_mirror row_mask:0xf bank_mask:0xf
	v_mov_b32_dpp v138, v136 row_mirror row_mask:0xf bank_mask:0xf
	v_pk_add_f32 v[154:155], v[136:137], v[138:139]
	v_mov_b32_e32 v136, v58
	v_mov_b32_e32 v137, v42
	v_pk_mul_f32 v[136:137], v[136:137], v[136:137]
	v_mov_b32_e32 v138, v26
	v_mov_b32_e32 v139, v10
	v_mov_b32_e32 v143, v11
	v_pk_mul_f32 v[138:139], v[138:139], v[138:139]
	v_pk_mul_f32 v[142:143], v[142:143], v[142:143]
	v_mov_b32_e32 v146, v140
	v_mov_b32_e32 v147, v136
	v_mov_b32_e32 v136, v141
	v_pk_add_f32 v[136:137], v[146:147], v[136:137]
	v_mov_b32_e32 v140, v142
	v_mov_b32_e32 v141, v138
	v_pk_add_f32 v[136:137], v[136:137], v[140:141]
	v_mov_b32_e32 v138, v143
	v_pk_add_f32 v[136:137], v[136:137], v[138:139]
	v_mov_b32_e32 v139, v1
	v_mov_b32_e32 v138, v1
	v_mov_b32_e32 v140, v61
	v_mov_b32_dpp v139, v137 quad_perm:[1,0,3,2] row_mask:0xf bank_mask:0xf
	v_mov_b32_dpp v138, v136 quad_perm:[1,0,3,2] row_mask:0xf bank_mask:0xf
	v_pk_add_f32 v[136:137], v[136:137], v[138:139]
	v_mov_b32_e32 v139, v1
	v_mov_b32_e32 v138, v1
	v_mov_b32_e32 v141, v45
	v_mov_b32_dpp v139, v137 quad_perm:[2,3,0,1] row_mask:0xf bank_mask:0xf
	v_mov_b32_dpp v138, v136 quad_perm:[2,3,0,1] row_mask:0xf bank_mask:0xf
	v_pk_add_f32 v[136:137], v[136:137], v[138:139]
	v_mov_b32_e32 v139, v1
	v_mov_b32_e32 v138, v1
	v_pk_mul_f32 v[140:141], v[140:141], v[140:141]
	v_mov_b32_dpp v139, v137 row_half_mirror row_mask:0xf bank_mask:0xf
	v_mov_b32_dpp v138, v136 row_half_mirror row_mask:0xf bank_mask:0xf
	v_pk_add_f32 v[136:137], v[136:137], v[138:139]
	v_mov_b32_e32 v139, v1
	v_mov_b32_e32 v138, v1
	v_mov_b32_e32 v142, v29
	v_mov_b32_dpp v139, v137 row_mirror row_mask:0xf bank_mask:0xf
	v_mov_b32_dpp v138, v136 row_mirror row_mask:0xf bank_mask:0xf
	v_pk_add_f32 v[150:151], v[136:137], v[138:139]
	v_mov_b32_e32 v136, v60
	v_mov_b32_e32 v137, v44
	v_pk_mul_f32 v[136:137], v[136:137], v[136:137]
	v_mov_b32_e32 v138, v28
	v_mov_b32_e32 v139, v12
	v_mov_b32_e32 v143, v13
	v_pk_mul_f32 v[138:139], v[138:139], v[138:139]
	v_pk_mul_f32 v[142:143], v[142:143], v[142:143]
	v_mov_b32_e32 v146, v140
	v_mov_b32_e32 v147, v136
	v_mov_b32_e32 v136, v141
	v_pk_add_f32 v[136:137], v[146:147], v[136:137]
	v_mov_b32_e32 v140, v142
	v_mov_b32_e32 v141, v138
	v_pk_add_f32 v[136:137], v[136:137], v[140:141]
	v_mov_b32_e32 v138, v143
	v_pk_add_f32 v[136:137], v[136:137], v[138:139]
	v_mov_b32_e32 v139, v1
	v_mov_b32_e32 v138, v1
	v_mov_b32_e32 v140, v63
	v_mov_b32_dpp v139, v137 quad_perm:[1,0,3,2] row_mask:0xf bank_mask:0xf
	v_mov_b32_dpp v138, v136 quad_perm:[1,0,3,2] row_mask:0xf bank_mask:0xf
	v_pk_add_f32 v[136:137], v[136:137], v[138:139]
	v_mov_b32_e32 v139, v1
	v_mov_b32_e32 v138, v1
	v_mov_b32_e32 v141, v47
	v_mov_b32_dpp v139, v137 quad_perm:[2,3,0,1] row_mask:0xf bank_mask:0xf
	v_mov_b32_dpp v138, v136 quad_perm:[2,3,0,1] row_mask:0xf bank_mask:0xf
	v_pk_add_f32 v[136:137], v[136:137], v[138:139]
	v_mov_b32_e32 v139, v1
	v_mov_b32_e32 v138, v1
	v_pk_mul_f32 v[140:141], v[140:141], v[140:141]
	v_mov_b32_dpp v139, v137 row_half_mirror row_mask:0xf bank_mask:0xf
	v_mov_b32_dpp v138, v136 row_half_mirror row_mask:0xf bank_mask:0xf
	v_pk_add_f32 v[136:137], v[136:137], v[138:139]
	v_mov_b32_e32 v139, v1
	v_mov_b32_e32 v138, v1
	v_mov_b32_e32 v142, v31
	v_mov_b32_dpp v139, v137 row_mirror row_mask:0xf bank_mask:0xf
	v_mov_b32_dpp v138, v136 row_mirror row_mask:0xf bank_mask:0xf
	v_pk_add_f32 v[146:147], v[136:137], v[138:139]
	v_mov_b32_e32 v136, v62
	v_mov_b32_e32 v137, v46
	v_pk_mul_f32 v[136:137], v[136:137], v[136:137]
	v_mov_b32_e32 v138, v30
	v_mov_b32_e32 v139, v14
	v_mov_b32_e32 v143, v15
	v_pk_mul_f32 v[138:139], v[138:139], v[138:139]
	v_pk_mul_f32 v[142:143], v[142:143], v[142:143]
	v_mov_b32_e32 v200, v140
	v_mov_b32_e32 v201, v136
	v_mov_b32_e32 v136, v141
	v_pk_add_f32 v[136:137], v[200:201], v[136:137]
	v_mov_b32_e32 v140, v142
	v_mov_b32_e32 v141, v138
	v_pk_add_f32 v[136:137], v[136:137], v[140:141]
	v_mov_b32_e32 v138, v143
	v_pk_add_f32 v[136:137], v[136:137], v[138:139]
	v_mov_b32_e32 v139, v1
	v_mov_b32_e32 v138, v1
	s_cmp_lt_i32 s0, 8
	v_mov_b32_dpp v139, v137 quad_perm:[1,0,3,2] row_mask:0xf bank_mask:0xf
	v_mov_b32_dpp v138, v136 quad_perm:[1,0,3,2] row_mask:0xf bank_mask:0xf
	v_pk_add_f32 v[136:137], v[136:137], v[138:139]
	v_mov_b32_e32 v139, v1
	v_mov_b32_e32 v138, v1
	v_mov_b32_e32 v200, v65
	v_mov_b32_dpp v139, v137 quad_perm:[2,3,0,1] row_mask:0xf bank_mask:0xf
	v_mov_b32_dpp v138, v136 quad_perm:[2,3,0,1] row_mask:0xf bank_mask:0xf
	v_pk_add_f32 v[136:137], v[136:137], v[138:139]
	v_mov_b32_e32 v139, v1
	v_mov_b32_e32 v138, v1
	v_mov_b32_e32 v201, v49
	v_mov_b32_dpp v139, v137 row_half_mirror row_mask:0xf bank_mask:0xf
	v_mov_b32_dpp v138, v136 row_half_mirror row_mask:0xf bank_mask:0xf
	v_pk_add_f32 v[136:137], v[136:137], v[138:139]
	v_mov_b32_e32 v139, v1
	v_mov_b32_e32 v138, v1
	s_waitcnt lgkmcnt(0)
; DEVI int crow(int r, int hi) { return (r & 3) + 8 * (r >> 2) + 4 * hi; }
; DEVI float xor1(float v) { return dppf<0xB1, 0xF>(v, v); }
;   DEVI void operator()(f32x16* acc, int mrow, int pn, int r32, int hi, char* slice) const {
;     ...
;       for (int r = 0; r < 16; ++r) {
;         float ss = 0.f;
; #pragma unroll
;         for (int j = 0; j < 4; ++j) ss += acc[j][r] * acc[j][r];
;         ss = half32_sum(ss, hi * 32 + r32);
;         rstd[r] = rsqrtf(ss * (1.f / 128.f) + EPS);
;       }
;       const float2* rope = (const float2*)(p->ws + OFF_ROPE);
; #pragma unroll
;       for (int j = 0; j < 4; ++j) {
;         const float g = gain[j * 32 + r32];
;         const int fi = (j & 1) * 16 + (r32 >> 1);
; #pragma unroll
;         for (int r = 0; r < 16; ++r) {
;           float v = acc[j][r] * rstd[r] * g;
;           if (latent) {
;             const int s = (mrow + crow(r, hi)) & (SEQ - 1);
;             const int idx = (j < 2) ? (s >> 6) : (s & 63);
;             const float2 cs = rope[idx * 32 + fi];
;             const float pr = xor1(v);
;             v = v * cs.x + (((r32 & 1) != DBG_BREAK) ? pr * cs.y : -pr * cs.y);
;           }
;           acc[j][r] = v;
	s_cselect_b32 s2, s60, s62
	v_mov_b32_dpp v139, v137 row_mirror row_mask:0xf bank_mask:0xf
	v_mov_b32_dpp v138, v136 row_mirror row_mask:0xf bank_mask:0xf
	v_pk_add_f32 v[140:141], v[136:137], v[138:139]
	v_mov_b32_e32 v136, v64
	v_mov_b32_e32 v137, v48
	v_pk_mul_f32 v[136:137], v[136:137], v[136:137]
	v_mov_b32_e32 v138, v32
	v_mov_b32_e32 v139, v16
	v_pk_mul_f32 v[200:201], v[200:201], v[200:201]
	v_mov_b32_e32 v202, v33
	v_mov_b32_e32 v203, v17
	s_cselect_b32 s1, s61, s63
	v_pk_mul_f32 v[138:139], v[138:139], v[138:139]
	v_pk_mul_f32 v[202:203], v[202:203], v[202:203]
	v_mov_b32_e32 v204, v200
	v_mov_b32_e32 v205, v136
	v_mov_b32_e32 v136, v201
	s_add_u32 s2, s2, s49
	v_pk_add_f32 v[136:137], v[204:205], v[136:137]
	v_mov_b32_e32 v200, v202
	v_mov_b32_e32 v201, v138
	s_addc_u32 s3, s1, 0
	v_pk_add_f32 v[136:137], v[136:137], v[200:201]
	global_load_dword v201, v0, s[2:3]
	v_mov_b32_e32 v138, v203
	v_pk_add_f32 v[136:137], v[136:137], v[138:139]
	v_mov_b32_e32 v139, v1
	v_mov_b32_e32 v138, v1
	ds_bpermute_b32 v165, v168, v163
	v_mov_b32_dpp v139, v137 quad_perm:[1,0,3,2] row_mask:0xf bank_mask:0xf
	v_mov_b32_dpp v138, v136 quad_perm:[1,0,3,2] row_mask:0xf bank_mask:0xf
	v_pk_add_f32 v[136:137], v[136:137], v[138:139]
	v_mov_b32_e32 v139, v1
	v_mov_b32_e32 v138, v1
	ds_bpermute_b32 v164, v168, v162
	v_mov_b32_dpp v139, v137 quad_perm:[2,3,0,1] row_mask:0xf bank_mask:0xf
	v_mov_b32_dpp v138, v136 quad_perm:[2,3,0,1] row_mask:0xf bank_mask:0xf
	v_pk_add_f32 v[136:137], v[136:137], v[138:139]
	v_mov_b32_e32 v139, v1
	v_mov_b32_e32 v138, v1
	ds_bpermute_b32 v161, v168, v159
	v_mov_b32_dpp v139, v137 row_half_mirror row_mask:0xf bank_mask:0xf
	v_mov_b32_dpp v138, v136 row_half_mirror row_mask:0xf bank_mask:0xf
	v_pk_add_f32 v[136:137], v[136:137], v[138:139]
	v_mov_b32_e32 v139, v1
	v_mov_b32_e32 v138, v1
	ds_bpermute_b32 v160, v168, v158
	v_mov_b32_dpp v139, v137 row_mirror row_mask:0xf bank_mask:0xf
	v_mov_b32_dpp v138, v136 row_mirror row_mask:0xf bank_mask:0xf
	v_pk_add_f32 v[136:137], v[136:137], v[138:139]
	ds_bpermute_b32 v157, v168, v155
	ds_bpermute_b32 v156, v168, v154
	ds_bpermute_b32 v153, v168, v151
	ds_bpermute_b32 v152, v168, v150
	ds_bpermute_b32 v149, v168, v147
	ds_bpermute_b32 v148, v168, v146
	ds_bpermute_b32 v143, v168, v141
	ds_bpermute_b32 v142, v168, v140
	ds_bpermute_b32 v139, v168, v137
	ds_bpermute_b32 v138, v168, v136
	v_mul_f32_e32 v50, v50, v199
	v_lshrrev_b32_e32 v202, 1, v198
	s_movk_i32 s1, 0x1fe0
	v_cmp_gt_f32_e32 vcc, s26, v144
	v_and_or_b32 v203, v202, s1, v169
	s_waitcnt vmcnt(0)
	v_mul_f32_e32 v50, v50, v201
	s_and_saveexec_b64 s[22:23], s[44:45]
	s_cbranch_execz .LBB0_2827
	v_lshlrev_b32_e32 v145, 3, v203
	global_load_dwordx2 v[204:205], v145, s[12:13]
	v_mov_b32_e32 v145, v50
	v_mov_b32_e32 v206, v50
	s_nop 0
	v_mov_b32_dpp v145, v145 quad_perm:[1,0,3,2] row_mask:0xf bank_mask:0xf
	v_cndmask_b32_e64 v207, v145, -v145, s[38:39]
	s_waitcnt vmcnt(0)
	v_mov_b32_e32 v250, v204
	v_mov_b32_e32 v251, v205
	v_pk_mul_f32 v[204:205], v[206:207], v[204:205]
	s_nop 0
	v_add_f32_e32 v50, v204, v205
.LBB0_2827:
	s_or_b64 exec, exec, s[22:23]
	v_mul_f32_e32 v145, 0x4b800000, v144
	v_cndmask_b32_e32 v144, v144, v145, vcc
	v_rsq_f32_e32 v144, v144
	s_nop 0
	v_mul_f32_e32 v145, 0x45800000, v144
	v_cndmask_b32_e32 v200, v144, v145, vcc
	v_mul_f32_e32 v51, v51, v200
	v_mul_f32_e32 v51, v51, v201
	s_and_saveexec_b64 s[22:23], s[44:45]
	s_cbranch_execz .LBB0_2829
	v_lshlrev_b32_e32 v144, 3, v203
	v_mov_b32_e32 v144, v250
	v_mov_b32_e32 v145, v251
	v_mov_b32_e32 v204, v51
	s_nop 1
	v_mov_b32_dpp v204, v204 quad_perm:[1,0,3,2] row_mask:0xf bank_mask:0xf
	v_cndmask_b32_e64 v205, v204, -v204, s[38:39]
	v_mov_b32_e32 v204, v51
	s_waitcnt vmcnt(0)
	v_pk_mul_f32 v[144:145], v[204:205], v[144:145]
	s_nop 0
	v_add_f32_e32 v51, v144, v145
.LBB0_2829:
	s_or_b64 exec, exec, s[22:23]
	s_waitcnt lgkmcnt(12)
	v_pk_add_f32 v[144:145], v[162:163], v[164:165]
	s_brev_b32 s22, 60
	v_pk_fma_f32 v[144:145], v[144:145], s[22:23], v[178:179] op_sel_hi:[1,0,0]
	s_nop 0
	v_mul_f32_e32 v162, 0x4b800000, v145
	v_cmp_gt_f32_e64 s[46:47], s26, v145
	v_cmp_gt_f32_e32 vcc, s26, v144
	s_nop 0
	v_cndmask_b32_e64 v145, v145, v162, s[46:47]
	v_rsq_f32_e32 v145, v145
	s_nop 0
	v_mul_f32_e32 v162, 0x45800000, v145
	v_cndmask_b32_e64 v162, v145, v162, s[46:47]
	v_mul_f32_e32 v52, v52, v162
	v_mul_f32_e32 v52, v52, v201
	s_and_saveexec_b64 s[22:23], s[44:45]
	s_cbranch_execz .LBB0_2831
	v_lshlrev_b32_e32 v145, 3, v203
	v_mov_b32_e32 v164, v250
	v_mov_b32_e32 v165, v251
	v_mov_b32_e32 v145, v52
	v_mov_b32_e32 v204, v52
	s_nop 0
	v_mov_b32_dpp v145, v145 quad_perm:[1,0,3,2] row_mask:0xf bank_mask:0xf
	v_cndmask_b32_e64 v205, v145, -v145, s[38:39]
	s_waitcnt vmcnt(0)
	v_pk_mul_f32 v[164:165], v[204:205], v[164:165]
	s_nop 0
	v_add_f32_e32 v52, v164, v165
.LBB0_2831:
	s_or_b64 exec, exec, s[22:23]
	v_mul_f32_e32 v145, 0x4b800000, v144
	v_cndmask_b32_e32 v144, v144, v145, vcc
	v_rsq_f32_e32 v144, v144
	s_nop 0
	v_mul_f32_e32 v145, 0x45800000, v144
	v_cndmask_b32_e32 v163, v144, v145, vcc
	v_mul_f32_e32 v53, v53, v163
	v_mul_f32_e32 v53, v53, v201
	s_and_saveexec_b64 s[22:23], s[44:45]
	s_cbranch_execz .LBB0_2833
	v_lshlrev_b32_e32 v144, 3, v203
	v_mov_b32_e32 v144, v250
	v_mov_b32_e32 v145, v251
	v_mov_b32_e32 v164, v53
	s_nop 1
	v_mov_b32_dpp v164, v164 quad_perm:[1,0,3,2] row_mask:0xf bank_mask:0xf
	v_cndmask_b32_e64 v165, v164, -v164, s[38:39]
	v_mov_b32_e32 v164, v53
	s_waitcnt vmcnt(0)
	v_pk_mul_f32 v[144:145], v[164:165], v[144:145]
	s_nop 0
	v_add_f32_e32 v53, v144, v145
; DEVI int crow(int r, int hi) { return (r & 3) + 8 * (r >> 2) + 4 * hi; }
; DEVI float xor1(float v) { return dppf<0xB1, 0xF>(v, v); }
;   DEVI void operator()(f32x16* acc, int mrow, int pn, int r32, int hi, char* slice) const {
;     ...
;       for (int j = 0; j < 4; ++j) {
;         const float g = gain[j * 32 + r32];
;         const int fi = (j & 1) * 16 + (r32 >> 1);
; #pragma unroll
;         for (int r = 0; r < 16; ++r) {
;           float v = acc[j][r] * rstd[r] * g;
;           if (latent) {
;             const int s = (mrow + crow(r, hi)) & (SEQ - 1);
;             const int idx = (j < 2) ? (s >> 6) : (s & 63);
;             const float2 cs = rope[idx * 32 + fi];
;             const float pr = xor1(v);
;             v = v * cs.x + (((r32 & 1) != DBG_BREAK) ? pr * cs.y : -pr * cs.y);
;           }
;           acc[j][r] = v;
.LBB0_2833:
	s_or_b64 exec, exec, s[22:23]
	s_waitcnt lgkmcnt(10)
	v_pk_add_f32 v[144:145], v[158:159], v[160:161]
	s_brev_b32 s22, 60
	v_pk_fma_f32 v[144:145], v[144:145], s[22:23], v[178:179] op_sel_hi:[1,0,0]
	s_nop 0
	v_mul_f32_e32 v158, 0x4b800000, v145
	v_cmp_gt_f32_e64 s[46:47], s26, v145
	v_cmp_gt_f32_e32 vcc, s26, v144
	s_nop 0
	v_cndmask_b32_e64 v145, v145, v158, s[46:47]
	v_rsq_f32_e32 v145, v145
	s_nop 0
	v_mul_f32_e32 v158, 0x45800000, v145
	v_cndmask_b32_e64 v158, v145, v158, s[46:47]
	v_mul_f32_e32 v54, v54, v158
	v_mul_f32_e32 v54, v54, v201
	s_and_saveexec_b64 s[22:23], s[44:45]
	s_cbranch_execz .LBB0_2835
	v_lshlrev_b32_e32 v145, 3, v203
	v_mov_b32_e32 v160, v250
	v_mov_b32_e32 v161, v251
	v_mov_b32_e32 v145, v54
	v_mov_b32_e32 v164, v54
	s_nop 0
	v_mov_b32_dpp v145, v145 quad_perm:[1,0,3,2] row_mask:0xf bank_mask:0xf
	v_cndmask_b32_e64 v165, v145, -v145, s[38:39]
	s_waitcnt vmcnt(0)
	v_pk_mul_f32 v[160:161], v[164:165], v[160:161]
	s_nop 0
	v_add_f32_e32 v54, v160, v161
.LBB0_2835:
	s_or_b64 exec, exec, s[22:23]
	v_mul_f32_e32 v145, 0x4b800000, v144
	v_cndmask_b32_e32 v144, v144, v145, vcc
	v_rsq_f32_e32 v144, v144
	s_nop 0
	v_mul_f32_e32 v145, 0x45800000, v144
	v_cndmask_b32_e32 v159, v144, v145, vcc
	v_mul_f32_e32 v55, v55, v159
	v_mul_f32_e32 v55, v55, v201
	s_and_saveexec_b64 s[22:23], s[44:45]
	s_cbranch_execz .LBB0_2837
	v_lshlrev_b32_e32 v144, 3, v203
	v_mov_b32_e32 v144, v250
	v_mov_b32_e32 v145, v251
	v_mov_b32_e32 v160, v55
	s_nop 1
	v_mov_b32_dpp v160, v160 quad_perm:[1,0,3,2] row_mask:0xf bank_mask:0xf
	v_cndmask_b32_e64 v161, v160, -v160, s[38:39]
	v_mov_b32_e32 v160, v55
	s_waitcnt vmcnt(0)
	v_pk_mul_f32 v[144:145], v[160:161], v[144:145]
	s_nop 0
	v_add_f32_e32 v55, v144, v145
.LBB0_2837:
	s_or_b64 exec, exec, s[22:23]
	s_waitcnt lgkmcnt(8)
	v_pk_add_f32 v[144:145], v[154:155], v[156:157]
	s_brev_b32 s22, 60
	v_pk_fma_f32 v[144:145], v[144:145], s[22:23], v[178:179] op_sel_hi:[1,0,0]
	s_nop 0
	v_mul_f32_e32 v154, 0x4b800000, v145
	v_cmp_gt_f32_e64 s[46:47], s26, v145
	v_cmp_gt_f32_e32 vcc, s26, v144
	s_nop 0
	v_cndmask_b32_e64 v145, v145, v154, s[46:47]
	v_rsq_f32_e32 v145, v145
	s_nop 0
	v_mul_f32_e32 v154, 0x45800000, v145
	v_cndmask_b32_e64 v154, v145, v154, s[46:47]
	v_mul_f32_e32 v56, v56, v154
	v_mul_f32_e32 v56, v56, v201
	s_and_saveexec_b64 s[22:23], s[44:45]
	s_cbranch_execz .LBB0_2839
	v_lshlrev_b32_e32 v145, 3, v203
	v_mov_b32_e32 v156, v250
	v_mov_b32_e32 v157, v251
	v_mov_b32_e32 v145, v56
	v_mov_b32_e32 v160, v56
	s_nop 0
	v_mov_b32_dpp v145, v145 quad_perm:[1,0,3,2] row_mask:0xf bank_mask:0xf
	v_cndmask_b32_e64 v161, v145, -v145, s[38:39]
	s_waitcnt vmcnt(0)
	v_pk_mul_f32 v[156:157], v[160:161], v[156:157]
	s_nop 0
	v_add_f32_e32 v56, v156, v157
.LBB0_2839:
	s_or_b64 exec, exec, s[22:23]
	v_mul_f32_e32 v145, 0x4b800000, v144
	v_cndmask_b32_e32 v144, v144, v145, vcc
	v_rsq_f32_e32 v144, v144
	s_nop 0
	v_mul_f32_e32 v145, 0x45800000, v144
	v_cndmask_b32_e32 v155, v144, v145, vcc
	v_mul_f32_e32 v57, v57, v155
	v_mul_f32_e32 v57, v57, v201
	s_and_saveexec_b64 s[22:23], s[44:45]
	s_cbranch_execz .LBB0_2841
	v_lshlrev_b32_e32 v144, 3, v203
	v_mov_b32_e32 v144, v250
	v_mov_b32_e32 v145, v251
	v_mov_b32_e32 v156, v57
	s_nop 1
	v_mov_b32_dpp v156, v156 quad_perm:[1,0,3,2] row_mask:0xf bank_mask:0xf
	v_cndmask_b32_e64 v157, v156, -v156, s[38:39]
	v_mov_b32_e32 v156, v57
	s_waitcnt vmcnt(0)
	v_pk_mul_f32 v[144:145], v[156:157], v[144:145]
	s_nop 0
	v_add_f32_e32 v57, v144, v145
.LBB0_2841:
	s_or_b64 exec, exec, s[22:23]
	s_waitcnt lgkmcnt(6)
	v_pk_add_f32 v[144:145], v[150:151], v[152:153]
	s_brev_b32 s22, 60
	v_pk_fma_f32 v[144:145], v[144:145], s[22:23], v[178:179] op_sel_hi:[1,0,0]
	s_nop 0
	v_mul_f32_e32 v150, 0x4b800000, v145
	v_cmp_gt_f32_e64 s[46:47], s26, v145
	v_cmp_gt_f32_e32 vcc, s26, v144
	s_nop 0
	v_cndmask_b32_e64 v145, v145, v150, s[46:47]
	v_rsq_f32_e32 v145, v145
	s_nop 0
	v_mul_f32_e32 v150, 0x45800000, v145
	v_cndmask_b32_e64 v151, v145, v150, s[46:47]
	v_mul_f32_e32 v58, v58, v151
	v_mul_f32_e32 v58, v58, v201
	s_and_saveexec_b64 s[22:23], s[44:45]
	s_cbranch_execz .LBB0_2843
	v_lshlrev_b32_e32 v145, 3, v203
	v_mov_b32_e32 v152, v250
	v_mov_b32_e32 v153, v251
	v_mov_b32_e32 v145, v58
	v_mov_b32_e32 v156, v58
	s_nop 0
	v_mov_b32_dpp v145, v145 quad_perm:[1,0,3,2] row_mask:0xf bank_mask:0xf
	v_cndmask_b32_e64 v157, v145, -v145, s[38:39]
	s_waitcnt vmcnt(0)
	v_pk_mul_f32 v[152:153], v[156:157], v[152:153]
	s_nop 0
	v_add_f32_e32 v58, v152, v153
.LBB0_2843:
	s_or_b64 exec, exec, s[22:23]
	v_mul_f32_e32 v145, 0x4b800000, v144
	v_cndmask_b32_e32 v144, v144, v145, vcc
	v_rsq_f32_e32 v144, v144
	s_nop 0
	v_mul_f32_e32 v145, 0x45800000, v144
	v_cndmask_b32_e32 v150, v144, v145, vcc
	v_mul_f32_e32 v59, v59, v150
	v_mul_f32_e32 v59, v59, v201
	s_and_saveexec_b64 s[22:23], s[44:45]
	s_cbranch_execz .LBB0_2845
	v_lshlrev_b32_e32 v144, 3, v203
	v_mov_b32_e32 v144, v250
	v_mov_b32_e32 v145, v251
	v_mov_b32_e32 v152, v59
	s_nop 1
	v_mov_b32_dpp v152, v152 quad_perm:[1,0,3,2] row_mask:0xf bank_mask:0xf
	v_cndmask_b32_e64 v153, v152, -v152, s[38:39]
	v_mov_b32_e32 v152, v59
	s_waitcnt vmcnt(0)
	v_pk_mul_f32 v[144:145], v[152:153], v[144:145]
	s_nop 0
	v_add_f32_e32 v59, v144, v145
; DEVI int crow(int r, int hi) { return (r & 3) + 8 * (r >> 2) + 4 * hi; }
; DEVI float xor1(float v) { return dppf<0xB1, 0xF>(v, v); }
;   DEVI void operator()(f32x16* acc, int mrow, int pn, int r32, int hi, char* slice) const {
;     ...
;       for (int j = 0; j < 4; ++j) {
;         const float g = gain[j * 32 + r32];
;         const int fi = (j & 1) * 16 + (r32 >> 1);
; #pragma unroll
;         for (int r = 0; r < 16; ++r) {
;           float v = acc[j][r] * rstd[r] * g;
;           if (latent) {
;             const int s = (mrow + crow(r, hi)) & (SEQ - 1);
;             const int idx = (j < 2) ? (s >> 6) : (s & 63);
;             const float2 cs = rope[idx * 32 + fi];
;             const float pr = xor1(v);
;             v = v * cs.x + (((r32 & 1) != DBG_BREAK) ? pr * cs.y : -pr * cs.y);
;           }
;           acc[j][r] = v;
.LBB0_2845:
	s_or_b64 exec, exec, s[22:23]
	s_waitcnt lgkmcnt(4)
	v_pk_add_f32 v[144:145], v[146:147], v[148:149]
	s_brev_b32 s22, 60
	v_pk_fma_f32 v[144:145], v[144:145], s[22:23], v[178:179] op_sel_hi:[1,0,0]
	s_nop 0
	v_mul_f32_e32 v146, 0x4b800000, v145
	v_cmp_gt_f32_e64 s[46:47], s26, v145
	v_cmp_gt_f32_e32 vcc, s26, v144
	s_nop 0
	v_cndmask_b32_e64 v145, v145, v146, s[46:47]
	v_rsq_f32_e32 v145, v145
	s_nop 0
	v_mul_f32_e32 v146, 0x45800000, v145
	v_cndmask_b32_e64 v145, v145, v146, s[46:47]
	v_mul_f32_e32 v60, v60, v145
	v_mul_f32_e32 v60, v60, v201
	s_and_saveexec_b64 s[22:23], s[44:45]
	s_cbranch_execz .LBB0_2847
	v_lshlrev_b32_e32 v146, 3, v203
	v_mov_b32_e32 v146, v250
	v_mov_b32_e32 v147, v251
	v_mov_b32_e32 v148, v60
	s_nop 1
	v_mov_b32_dpp v148, v148 quad_perm:[1,0,3,2] row_mask:0xf bank_mask:0xf
	v_cndmask_b32_e64 v149, v148, -v148, s[38:39]
	v_mov_b32_e32 v148, v60
	s_waitcnt vmcnt(0)
	v_pk_mul_f32 v[146:147], v[148:149], v[146:147]
	s_nop 0
	v_add_f32_e32 v60, v146, v147
.LBB0_2847:
	s_or_b64 exec, exec, s[22:23]
	v_mul_f32_e32 v146, 0x4b800000, v144
	v_cndmask_b32_e32 v144, v144, v146, vcc
	v_rsq_f32_e32 v144, v144
	s_nop 0
	v_mul_f32_e32 v146, 0x45800000, v144
	v_cndmask_b32_e32 v144, v144, v146, vcc
	v_mul_f32_e32 v61, v61, v144
	v_mul_f32_e32 v61, v61, v201
	s_and_saveexec_b64 s[22:23], s[44:45]
	s_cbranch_execz .LBB0_2849
	v_lshlrev_b32_e32 v146, 3, v203
	v_mov_b32_e32 v146, v250
	v_mov_b32_e32 v147, v251
	v_mov_b32_e32 v148, v61
	s_nop 1
	v_mov_b32_dpp v148, v148 quad_perm:[1,0,3,2] row_mask:0xf bank_mask:0xf
	v_cndmask_b32_e64 v149, v148, -v148, s[38:39]
	v_mov_b32_e32 v148, v61
	s_waitcnt vmcnt(0)
	v_pk_mul_f32 v[146:147], v[148:149], v[146:147]
	s_nop 0
	v_add_f32_e32 v61, v146, v147
.LBB0_2849:
	s_or_b64 exec, exec, s[22:23]
	s_waitcnt lgkmcnt(2)
	v_pk_add_f32 v[140:141], v[140:141], v[142:143]
	s_brev_b32 s22, 60
	v_pk_fma_f32 v[140:141], v[140:141], s[22:23], v[178:179] op_sel_hi:[1,0,0]
	s_nop 0
	v_mul_f32_e32 v142, 0x4b800000, v141
	v_cmp_gt_f32_e64 s[46:47], s26, v141
	v_cmp_gt_f32_e32 vcc, s26, v140
	s_nop 0
	v_cndmask_b32_e64 v141, v141, v142, s[46:47]
	v_rsq_f32_e32 v141, v141
	s_nop 0
	v_mul_f32_e32 v142, 0x45800000, v141
	v_cndmask_b32_e64 v141, v141, v142, s[46:47]
	v_mul_f32_e32 v62, v62, v141
	v_mul_f32_e32 v62, v62, v201
	s_and_saveexec_b64 s[22:23], s[44:45]
	s_cbranch_execz .LBB0_2851
	v_lshlrev_b32_e32 v142, 3, v203
	v_mov_b32_e32 v142, v250
	v_mov_b32_e32 v143, v251
	v_mov_b32_e32 v146, v62
	s_nop 1
	v_mov_b32_dpp v146, v146 quad_perm:[1,0,3,2] row_mask:0xf bank_mask:0xf
	v_cndmask_b32_e64 v147, v146, -v146, s[38:39]
	v_mov_b32_e32 v146, v62
	s_waitcnt vmcnt(0)
	v_pk_mul_f32 v[142:143], v[146:147], v[142:143]
	s_nop 0
	v_add_f32_e32 v62, v142, v143
.LBB0_2851:
	s_or_b64 exec, exec, s[22:23]
	v_mul_f32_e32 v142, 0x4b800000, v140
	v_cndmask_b32_e32 v140, v140, v142, vcc
	v_rsq_f32_e32 v140, v140
	s_nop 0
	v_mul_f32_e32 v142, 0x45800000, v140
	v_cndmask_b32_e32 v140, v140, v142, vcc
	v_mul_f32_e32 v63, v63, v140
	v_mul_f32_e32 v63, v63, v201
	s_and_saveexec_b64 s[22:23], s[44:45]
	s_cbranch_execz .LBB0_2853
	v_lshlrev_b32_e32 v142, 3, v203
	v_mov_b32_e32 v142, v250
	v_mov_b32_e32 v143, v251
	v_mov_b32_e32 v146, v63
	s_nop 1
	v_mov_b32_dpp v146, v146 quad_perm:[1,0,3,2] row_mask:0xf bank_mask:0xf
	v_cndmask_b32_e64 v147, v146, -v146, s[38:39]
	v_mov_b32_e32 v146, v63
	s_waitcnt vmcnt(0)
	v_pk_mul_f32 v[142:143], v[146:147], v[142:143]
	s_nop 0
	v_add_f32_e32 v63, v142, v143
.LBB0_2853:
	s_or_b64 exec, exec, s[22:23]
	s_waitcnt lgkmcnt(0)
	v_pk_add_f32 v[136:137], v[136:137], v[138:139]
	s_brev_b32 s22, 60
	v_pk_fma_f32 v[136:137], v[136:137], s[22:23], v[178:179] op_sel_hi:[1,0,0]
	s_nop 0
	v_mul_f32_e32 v138, 0x4b800000, v137
	v_cmp_gt_f32_e64 s[46:47], s26, v137
	v_cmp_gt_f32_e32 vcc, s26, v136
	s_nop 0
	v_cndmask_b32_e64 v137, v137, v138, s[46:47]
	v_rsq_f32_e32 v137, v137
	s_nop 0
	v_mul_f32_e32 v138, 0x45800000, v137
	v_cndmask_b32_e64 v139, v137, v138, s[46:47]
	v_mul_f32_e32 v64, v64, v139
	v_mul_f32_e32 v64, v201, v64
	s_and_saveexec_b64 s[22:23], s[44:45]
	s_cbranch_execz .LBB0_2855
	v_lshlrev_b32_e32 v137, 3, v203
	v_mov_b32_e32 v142, v250
	v_mov_b32_e32 v143, v251
	v_mov_b32_e32 v137, v64
	v_mov_b32_e32 v146, v64
	s_nop 0
	v_mov_b32_dpp v137, v137 quad_perm:[1,0,3,2] row_mask:0xf bank_mask:0xf
	v_cndmask_b32_e64 v147, v137, -v137, s[38:39]
	s_waitcnt vmcnt(0)
	v_pk_mul_f32 v[142:143], v[146:147], v[142:143]
	s_nop 0
	v_add_f32_e32 v64, v142, v143
.LBB0_2855:
	s_or_b64 exec, exec, s[22:23]
	v_mul_f32_e32 v137, 0x4b800000, v136
	v_cndmask_b32_e32 v136, v136, v137, vcc
	v_rsq_f32_e32 v136, v136
	s_nop 0
	v_mul_f32_e32 v137, 0x45800000, v136
	v_cndmask_b32_e32 v138, v136, v137, vcc
	v_mul_f32_e32 v65, v65, v138
	v_mul_f32_e32 v65, v201, v65
	s_and_saveexec_b64 s[22:23], s[44:45]
	s_cbranch_execz .LBB0_2857
	v_lshlrev_b32_e32 v136, 3, v203
	v_mov_b32_e32 v136, v250
	v_mov_b32_e32 v137, v251
	v_mov_b32_e32 v142, v65
	s_nop 1
	v_mov_b32_dpp v142, v142 quad_perm:[1,0,3,2] row_mask:0xf bank_mask:0xf
	v_cndmask_b32_e64 v143, v142, -v142, s[38:39]
	v_mov_b32_e32 v142, v65
	s_waitcnt vmcnt(0)
	v_pk_mul_f32 v[136:137], v[142:143], v[136:137]
	s_nop 0
	v_add_f32_e32 v65, v136, v137
.LBB0_2857:
	s_or_b64 exec, exec, s[22:23]
	v_lshl_add_u64 v[136:137], s[2:3], 0, v[0:1]
	global_load_dword v143, v[136:137], off offset:128
	v_mul_f32_e32 v34, v34, v199
	v_and_or_b32 v142, v202, s1, v171
	s_waitcnt vmcnt(0)
	v_mul_f32_e32 v34, v34, v143
	s_and_saveexec_b64 s[2:3], s[44:45]
	s_cbranch_execz .LBB0_2859
	v_lshlrev_b32_e32 v146, 3, v142
	global_load_dwordx2 v[146:147], v146, s[12:13]
	v_mov_b32_e32 v148, v34
	s_nop 1
	v_mov_b32_dpp v148, v148 quad_perm:[1,0,3,2] row_mask:0xf bank_mask:0xf
	v_cndmask_b32_e64 v149, v148, -v148, s[38:39]
	v_mov_b32_e32 v148, v34
	s_waitcnt vmcnt(0)
	v_mov_b32_e32 v250, v146
	v_mov_b32_e32 v251, v147
	v_pk_mul_f32 v[146:147], v[148:149], v[146:147]
	s_nop 0
	v_add_f32_e32 v34, v146, v147
; DEVI int crow(int r, int hi) { return (r & 3) + 8 * (r >> 2) + 4 * hi; }
; DEVI float xor1(float v) { return dppf<0xB1, 0xF>(v, v); }
;   DEVI void operator()(f32x16* acc, int mrow, int pn, int r32, int hi, char* slice) const {
;     ...
;       for (int j = 0; j < 4; ++j) {
;         const float g = gain[j * 32 + r32];
;         const int fi = (j & 1) * 16 + (r32 >> 1);
; #pragma unroll
;         for (int r = 0; r < 16; ++r) {
;           float v = acc[j][r] * rstd[r] * g;
;           if (latent) {
;             const int s = (mrow + crow(r, hi)) & (SEQ - 1);
;             const int idx = (j < 2) ? (s >> 6) : (s & 63);
;             const float2 cs = rope[idx * 32 + fi];
;             const float pr = xor1(v);
;             v = v * cs.x + (((r32 & 1) != DBG_BREAK) ? pr * cs.y : -pr * cs.y);
;           }
;           acc[j][r] = v;
.LBB0_2859:
	s_or_b64 exec, exec, s[2:3]
	v_mul_f32_e32 v35, v35, v200
	v_mul_f32_e32 v35, v35, v143
	s_and_saveexec_b64 s[2:3], s[44:45]
	s_cbranch_execz .LBB0_2861
	v_lshlrev_b32_e32 v146, 3, v142
	v_mov_b32_e32 v146, v250
	v_mov_b32_e32 v147, v251
	v_mov_b32_e32 v148, v35
	s_nop 1
	v_mov_b32_dpp v148, v148 quad_perm:[1,0,3,2] row_mask:0xf bank_mask:0xf
	v_cndmask_b32_e64 v149, v148, -v148, s[38:39]
	v_mov_b32_e32 v148, v35
	s_waitcnt vmcnt(0)
	v_pk_mul_f32 v[146:147], v[148:149], v[146:147]
	s_nop 0
	v_add_f32_e32 v35, v146, v147
.LBB0_2861:
	s_or_b64 exec, exec, s[2:3]
	v_mul_f32_e32 v36, v36, v162
	v_mul_f32_e32 v36, v36, v143
	s_and_saveexec_b64 s[2:3], s[44:45]
	s_cbranch_execz .LBB0_2863
	v_lshlrev_b32_e32 v146, 3, v142
	v_mov_b32_e32 v146, v250
	v_mov_b32_e32 v147, v251
	v_mov_b32_e32 v148, v36
	s_nop 1
	v_mov_b32_dpp v148, v148 quad_perm:[1,0,3,2] row_mask:0xf bank_mask:0xf
	v_cndmask_b32_e64 v149, v148, -v148, s[38:39]
	v_mov_b32_e32 v148, v36
	s_waitcnt vmcnt(0)
	v_pk_mul_f32 v[146:147], v[148:149], v[146:147]
	s_nop 0
	v_add_f32_e32 v36, v146, v147
.LBB0_2863:
	s_or_b64 exec, exec, s[2:3]
	v_mul_f32_e32 v37, v37, v163
	v_mul_f32_e32 v37, v37, v143
	s_and_saveexec_b64 s[2:3], s[44:45]
	s_cbranch_execz .LBB0_2865
	v_lshlrev_b32_e32 v146, 3, v142
	v_mov_b32_e32 v146, v250
	v_mov_b32_e32 v147, v251
	v_mov_b32_e32 v148, v37
	s_nop 1
	v_mov_b32_dpp v148, v148 quad_perm:[1,0,3,2] row_mask:0xf bank_mask:0xf
	v_cndmask_b32_e64 v149, v148, -v148, s[38:39]
	v_mov_b32_e32 v148, v37
	s_waitcnt vmcnt(0)
	v_pk_mul_f32 v[146:147], v[148:149], v[146:147]
	s_nop 0
	v_add_f32_e32 v37, v146, v147
.LBB0_2865:
	s_or_b64 exec, exec, s[2:3]
	v_mul_f32_e32 v38, v38, v158
	v_mul_f32_e32 v38, v38, v143
	s_and_saveexec_b64 s[2:3], s[44:45]
	s_cbranch_execz .LBB0_2867
	v_lshlrev_b32_e32 v146, 3, v142
	v_mov_b32_e32 v146, v250
	v_mov_b32_e32 v147, v251
	v_mov_b32_e32 v148, v38
	s_nop 1
	v_mov_b32_dpp v148, v148 quad_perm:[1,0,3,2] row_mask:0xf bank_mask:0xf
	v_cndmask_b32_e64 v149, v148, -v148, s[38:39]
	v_mov_b32_e32 v148, v38
	s_waitcnt vmcnt(0)
	v_pk_mul_f32 v[146:147], v[148:149], v[146:147]
	s_nop 0
	v_add_f32_e32 v38, v146, v147
.LBB0_2867:
	s_or_b64 exec, exec, s[2:3]
	v_mul_f32_e32 v39, v39, v159
	v_mul_f32_e32 v39, v39, v143
	s_and_saveexec_b64 s[2:3], s[44:45]
	s_cbranch_execz .LBB0_2869
	v_lshlrev_b32_e32 v146, 3, v142
	v_mov_b32_e32 v146, v250
	v_mov_b32_e32 v147, v251
	v_mov_b32_e32 v148, v39
	s_nop 1
	v_mov_b32_dpp v148, v148 quad_perm:[1,0,3,2] row_mask:0xf bank_mask:0xf
	v_cndmask_b32_e64 v149, v148, -v148, s[38:39]
	v_mov_b32_e32 v148, v39
	s_waitcnt vmcnt(0)
	v_pk_mul_f32 v[146:147], v[148:149], v[146:147]
	s_nop 0
	v_add_f32_e32 v39, v146, v147
.LBB0_2869:
	s_or_b64 exec, exec, s[2:3]
	v_mul_f32_e32 v40, v40, v154
	v_mul_f32_e32 v40, v40, v143
	s_and_saveexec_b64 s[2:3], s[44:45]
	s_cbranch_execz .LBB0_2871
	v_lshlrev_b32_e32 v146, 3, v142
	v_mov_b32_e32 v146, v250
	v_mov_b32_e32 v147, v251
	v_mov_b32_e32 v148, v40
	s_nop 1
	v_mov_b32_dpp v148, v148 quad_perm:[1,0,3,2] row_mask:0xf bank_mask:0xf
	v_cndmask_b32_e64 v149, v148, -v148, s[38:39]
	v_mov_b32_e32 v148, v40
	s_waitcnt vmcnt(0)
	v_pk_mul_f32 v[146:147], v[148:149], v[146:147]
	s_nop 0
	v_add_f32_e32 v40, v146, v147
.LBB0_2871:
	s_or_b64 exec, exec, s[2:3]
	v_mul_f32_e32 v41, v41, v155
	v_mul_f32_e32 v41, v41, v143
	s_and_saveexec_b64 s[2:3], s[44:45]
	s_cbranch_execz .LBB0_2873
	v_lshlrev_b32_e32 v146, 3, v142
	v_mov_b32_e32 v146, v250
	v_mov_b32_e32 v147, v251
	v_mov_b32_e32 v148, v41
	s_nop 1
	v_mov_b32_dpp v148, v148 quad_perm:[1,0,3,2] row_mask:0xf bank_mask:0xf
	v_cndmask_b32_e64 v149, v148, -v148, s[38:39]
	v_mov_b32_e32 v148, v41
	s_waitcnt vmcnt(0)
	v_pk_mul_f32 v[146:147], v[148:149], v[146:147]
	s_nop 0
	v_add_f32_e32 v41, v146, v147
.LBB0_2873:
	s_or_b64 exec, exec, s[2:3]
	v_mul_f32_e32 v42, v42, v151
	v_mul_f32_e32 v42, v42, v143
	s_and_saveexec_b64 s[2:3], s[44:45]
	s_cbranch_execz .LBB0_2875
	v_lshlrev_b32_e32 v146, 3, v142
	v_mov_b32_e32 v146, v250
	v_mov_b32_e32 v147, v251
	v_mov_b32_e32 v148, v42
	s_nop 1
	v_mov_b32_dpp v148, v148 quad_perm:[1,0,3,2] row_mask:0xf bank_mask:0xf
	v_cndmask_b32_e64 v149, v148, -v148, s[38:39]
	v_mov_b32_e32 v148, v42
	s_waitcnt vmcnt(0)
	v_pk_mul_f32 v[146:147], v[148:149], v[146:147]
	s_nop 0
	v_add_f32_e32 v42, v146, v147
.LBB0_2875:
	s_or_b64 exec, exec, s[2:3]
	v_mul_f32_e32 v43, v43, v150
	v_mul_f32_e32 v43, v43, v143
	s_and_saveexec_b64 s[2:3], s[44:45]
	s_cbranch_execz .LBB0_2877
	v_lshlrev_b32_e32 v146, 3, v142
	v_mov_b32_e32 v146, v250
	v_mov_b32_e32 v147, v251
	v_mov_b32_e32 v148, v43
	s_nop 1
	v_mov_b32_dpp v148, v148 quad_perm:[1,0,3,2] row_mask:0xf bank_mask:0xf
	v_cndmask_b32_e64 v149, v148, -v148, s[38:39]
	v_mov_b32_e32 v148, v43
	s_waitcnt vmcnt(0)
	v_pk_mul_f32 v[146:147], v[148:149], v[146:147]
	s_nop 0
	v_add_f32_e32 v43, v146, v147
.LBB0_2877:
	s_or_b64 exec, exec, s[2:3]
	v_mul_f32_e32 v44, v44, v145
	v_mul_f32_e32 v44, v44, v143
	s_and_saveexec_b64 s[2:3], s[44:45]
	s_cbranch_execz .LBB0_2879
	v_lshlrev_b32_e32 v146, 3, v142
	v_mov_b32_e32 v146, v250
	v_mov_b32_e32 v147, v251
	v_mov_b32_e32 v148, v44
	s_nop 1
	v_mov_b32_dpp v148, v148 quad_perm:[1,0,3,2] row_mask:0xf bank_mask:0xf
	v_cndmask_b32_e64 v149, v148, -v148, s[38:39]
	v_mov_b32_e32 v148, v44
	s_waitcnt vmcnt(0)
	v_pk_mul_f32 v[146:147], v[148:149], v[146:147]
	s_nop 0
	v_add_f32_e32 v44, v146, v147
; DEVI int crow(int r, int hi) { return (r & 3) + 8 * (r >> 2) + 4 * hi; }
; DEVI float xor1(float v) { return dppf<0xB1, 0xF>(v, v); }
;   DEVI void operator()(f32x16* acc, int mrow, int pn, int r32, int hi, char* slice) const {
;     ...
;       for (int j = 0; j < 4; ++j) {
;         const float g = gain[j * 32 + r32];
;         const int fi = (j & 1) * 16 + (r32 >> 1);
; #pragma unroll
;         for (int r = 0; r < 16; ++r) {
;           float v = acc[j][r] * rstd[r] * g;
;           if (latent) {
;             const int s = (mrow + crow(r, hi)) & (SEQ - 1);
;             const int idx = (j < 2) ? (s >> 6) : (s & 63);
;             const float2 cs = rope[idx * 32 + fi];
;             const float pr = xor1(v);
;             v = v * cs.x + (((r32 & 1) != DBG_BREAK) ? pr * cs.y : -pr * cs.y);
;           }
;           acc[j][r] = v;
.LBB0_2879:
	s_or_b64 exec, exec, s[2:3]
	v_mul_f32_e32 v45, v45, v144
	v_mul_f32_e32 v45, v45, v143
	s_and_saveexec_b64 s[2:3], s[44:45]
	s_cbranch_execz .LBB0_2881
	v_lshlrev_b32_e32 v146, 3, v142
	v_mov_b32_e32 v146, v250
	v_mov_b32_e32 v147, v251
	v_mov_b32_e32 v148, v45
	s_nop 1
	v_mov_b32_dpp v148, v148 quad_perm:[1,0,3,2] row_mask:0xf bank_mask:0xf
	v_cndmask_b32_e64 v149, v148, -v148, s[38:39]
	v_mov_b32_e32 v148, v45
	s_waitcnt vmcnt(0)
	v_pk_mul_f32 v[146:147], v[148:149], v[146:147]
	s_nop 0
	v_add_f32_e32 v45, v146, v147
.LBB0_2881:
	s_or_b64 exec, exec, s[2:3]
	v_mul_f32_e32 v46, v46, v141
	v_mul_f32_e32 v46, v46, v143
	s_and_saveexec_b64 s[2:3], s[44:45]
	s_cbranch_execz .LBB0_2883
	v_lshlrev_b32_e32 v146, 3, v142
	v_mov_b32_e32 v146, v250
	v_mov_b32_e32 v147, v251
	v_mov_b32_e32 v148, v46
	s_nop 1
	v_mov_b32_dpp v148, v148 quad_perm:[1,0,3,2] row_mask:0xf bank_mask:0xf
	v_cndmask_b32_e64 v149, v148, -v148, s[38:39]
	v_mov_b32_e32 v148, v46
	s_waitcnt vmcnt(0)
	v_pk_mul_f32 v[146:147], v[148:149], v[146:147]
	s_nop 0
	v_add_f32_e32 v46, v146, v147
.LBB0_2883:
	s_or_b64 exec, exec, s[2:3]
	v_mul_f32_e32 v47, v47, v140
	v_mul_f32_e32 v47, v47, v143
	s_and_saveexec_b64 s[2:3], s[44:45]
	s_cbranch_execz .LBB0_2885
	v_lshlrev_b32_e32 v146, 3, v142
	v_mov_b32_e32 v146, v250
	v_mov_b32_e32 v147, v251
	v_mov_b32_e32 v148, v47
	s_nop 1
	v_mov_b32_dpp v148, v148 quad_perm:[1,0,3,2] row_mask:0xf bank_mask:0xf
	v_cndmask_b32_e64 v149, v148, -v148, s[38:39]
	v_mov_b32_e32 v148, v47
	s_waitcnt vmcnt(0)
	v_pk_mul_f32 v[146:147], v[148:149], v[146:147]
	s_nop 0
	v_add_f32_e32 v47, v146, v147
.LBB0_2885:
	s_or_b64 exec, exec, s[2:3]
	v_mul_f32_e32 v48, v48, v139
	v_mul_f32_e32 v48, v48, v143
	s_and_saveexec_b64 s[2:3], s[44:45]
	s_cbranch_execz .LBB0_2887
	v_lshlrev_b32_e32 v146, 3, v142
	v_mov_b32_e32 v146, v250
	v_mov_b32_e32 v147, v251
	v_mov_b32_e32 v148, v48
	s_nop 1
	v_mov_b32_dpp v148, v148 quad_perm:[1,0,3,2] row_mask:0xf bank_mask:0xf
	v_cndmask_b32_e64 v149, v148, -v148, s[38:39]
	v_mov_b32_e32 v148, v48
	s_waitcnt vmcnt(0)
	v_pk_mul_f32 v[146:147], v[148:149], v[146:147]
	s_nop 0
	v_add_f32_e32 v48, v146, v147
.LBB0_2887:
	s_or_b64 exec, exec, s[2:3]
	v_mul_f32_e32 v49, v49, v138
	v_mul_f32_e32 v49, v49, v143
	s_and_saveexec_b64 s[2:3], s[44:45]
	s_cbranch_execz .LBB0_2889
	v_lshlrev_b32_e32 v142, 3, v142
	v_mov_b32_e32 v142, v250
	v_mov_b32_e32 v143, v251
	v_mov_b32_e32 v146, v49
	s_nop 1
	v_mov_b32_dpp v146, v146 quad_perm:[1,0,3,2] row_mask:0xf bank_mask:0xf
	v_cndmask_b32_e64 v147, v146, -v146, s[38:39]
	v_mov_b32_e32 v146, v49
	s_waitcnt vmcnt(0)
	v_pk_mul_f32 v[142:143], v[146:147], v[142:143]
	s_nop 0
	v_add_f32_e32 v49, v142, v143
.LBB0_2889:
	s_or_b64 exec, exec, s[2:3]
	global_load_dword v146, v[136:137], off offset:256
	v_or_b32_e32 v142, v198, v170
	v_mul_f32_e32 v18, v18, v199
	v_lshlrev_b32_e32 v142, 5, v142
	s_movk_i32 s1, 0x480
	v_and_or_b32 v143, v142, s1, v169
	s_waitcnt vmcnt(0)
	v_mul_f32_e32 v18, v18, v146
	s_and_saveexec_b64 s[2:3], s[44:45]
	s_cbranch_execz .LBB0_2891
	v_lshlrev_b32_e32 v147, 3, v143
	global_load_dwordx2 v[244:245], v147, s[12:13] offset:256
	global_load_dwordx2 v[246:247], v147, s[12:13] offset:512
	global_load_dwordx2 v[248:249], v147, s[12:13] offset:768
	global_load_dwordx2 v[148:149], v147, s[12:13]
	v_mov_b32_e32 v147, v18
	v_mov_b32_e32 v152, v18
	s_nop 0
	v_mov_b32_dpp v147, v147 quad_perm:[1,0,3,2] row_mask:0xf bank_mask:0xf
	v_cndmask_b32_e64 v153, v147, -v147, s[38:39]
	s_waitcnt vmcnt(0)
	v_pk_mul_f32 v[148:149], v[152:153], v[148:149]
	s_nop 0
	v_add_f32_e32 v18, v148, v149
.LBB0_2891:
	s_or_b64 exec, exec, s[2:3]
	v_mul_f32_e32 v19, v19, v200
	v_mul_f32_e32 v19, v19, v146
	s_and_saveexec_b64 s[2:3], s[44:45]
	s_cbranch_execz .LBB0_2893
	v_lshlrev_b32_e32 v147, 3, v143
	v_mov_b32_e32 v148, v244
	v_mov_b32_e32 v149, v245
	v_mov_b32_e32 v147, v19
	v_mov_b32_e32 v152, v19
	s_nop 0
	v_mov_b32_dpp v147, v147 quad_perm:[1,0,3,2] row_mask:0xf bank_mask:0xf
	v_cndmask_b32_e64 v153, v147, -v147, s[38:39]
	s_waitcnt vmcnt(0)
	v_pk_mul_f32 v[148:149], v[152:153], v[148:149]
	s_nop 0
	v_add_f32_e32 v19, v148, v149
.LBB0_2893:
	s_or_b64 exec, exec, s[2:3]
	v_mul_f32_e32 v20, v20, v162
	v_mul_f32_e32 v20, v20, v146
	s_and_saveexec_b64 s[2:3], s[44:45]
	s_cbranch_execz .LBB0_2895
	v_lshlrev_b32_e32 v147, 3, v143
	v_mov_b32_e32 v148, v246
	v_mov_b32_e32 v149, v247
	v_mov_b32_e32 v147, v20
	v_mov_b32_e32 v152, v20
	s_nop 0
	v_mov_b32_dpp v147, v147 quad_perm:[1,0,3,2] row_mask:0xf bank_mask:0xf
	v_cndmask_b32_e64 v153, v147, -v147, s[38:39]
	s_waitcnt vmcnt(0)
	v_pk_mul_f32 v[148:149], v[152:153], v[148:149]
	s_nop 0
	v_add_f32_e32 v20, v148, v149
.LBB0_2895:
	s_or_b64 exec, exec, s[2:3]
	v_mul_f32_e32 v21, v21, v163
	v_mul_f32_e32 v21, v21, v146
	s_and_saveexec_b64 s[2:3], s[44:45]
	s_cbranch_execz .LBB0_2897
	v_lshlrev_b32_e32 v147, 3, v143
	v_mov_b32_e32 v148, v248
	v_mov_b32_e32 v149, v249
	v_mov_b32_e32 v147, v21
	v_mov_b32_e32 v152, v21
	s_nop 0
	v_mov_b32_dpp v147, v147 quad_perm:[1,0,3,2] row_mask:0xf bank_mask:0xf
	v_cndmask_b32_e64 v153, v147, -v147, s[38:39]
	s_waitcnt vmcnt(0)
	v_pk_mul_f32 v[148:149], v[152:153], v[148:149]
	s_nop 0
	v_add_f32_e32 v21, v148, v149
.LBB0_2897:
	s_or_b64 exec, exec, s[2:3]
	v_mul_f32_e32 v22, v22, v158
	v_mul_f32_e32 v22, v22, v146
	s_and_saveexec_b64 s[2:3], s[44:45]
	s_cbranch_execz .LBB0_2899
	v_lshlrev_b32_e32 v147, 3, v143
	global_load_dwordx2 v[244:245], v147, s[12:13] offset:2304
	global_load_dwordx2 v[246:247], v147, s[12:13] offset:2560
	global_load_dwordx2 v[248:249], v147, s[12:13] offset:2816
	global_load_dwordx2 v[148:149], v147, s[12:13] offset:2048
	v_mov_b32_e32 v147, v22
	v_mov_b32_e32 v152, v22
	s_nop 0
	v_mov_b32_dpp v147, v147 quad_perm:[1,0,3,2] row_mask:0xf bank_mask:0xf
	v_cndmask_b32_e64 v153, v147, -v147, s[38:39]
	s_waitcnt vmcnt(0)
	v_pk_mul_f32 v[148:149], v[152:153], v[148:149]
	s_nop 0
	v_add_f32_e32 v22, v148, v149
; DEVI int crow(int r, int hi) { return (r & 3) + 8 * (r >> 2) + 4 * hi; }
; DEVI float xor1(float v) { return dppf<0xB1, 0xF>(v, v); }
;   DEVI void operator()(f32x16* acc, int mrow, int pn, int r32, int hi, char* slice) const {
;     ...
;       for (int j = 0; j < 4; ++j) {
;         const float g = gain[j * 32 + r32];
;         const int fi = (j & 1) * 16 + (r32 >> 1);
; #pragma unroll
;         for (int r = 0; r < 16; ++r) {
;           float v = acc[j][r] * rstd[r] * g;
;           if (latent) {
;             const int s = (mrow + crow(r, hi)) & (SEQ - 1);
;             const int idx = (j < 2) ? (s >> 6) : (s & 63);
;             const float2 cs = rope[idx * 32 + fi];
;             const float pr = xor1(v);
;             v = v * cs.x + (((r32 & 1) != DBG_BREAK) ? pr * cs.y : -pr * cs.y);
;           }
;           acc[j][r] = v;
.LBB0_2899:
	s_or_b64 exec, exec, s[2:3]
	v_mul_f32_e32 v23, v23, v159
	v_mul_f32_e32 v23, v23, v146
	s_and_saveexec_b64 s[2:3], s[44:45]
	s_cbranch_execz .LBB0_2901
	v_lshlrev_b32_e32 v147, 3, v143
	v_mov_b32_e32 v148, v244
	v_mov_b32_e32 v149, v245
	v_mov_b32_e32 v147, v23
	v_mov_b32_e32 v152, v23
	s_nop 0
	v_mov_b32_dpp v147, v147 quad_perm:[1,0,3,2] row_mask:0xf bank_mask:0xf
	v_cndmask_b32_e64 v153, v147, -v147, s[38:39]
	s_waitcnt vmcnt(0)
	v_pk_mul_f32 v[148:149], v[152:153], v[148:149]
	s_nop 0
	v_add_f32_e32 v23, v148, v149
.LBB0_2901:
	s_or_b64 exec, exec, s[2:3]
	v_mul_f32_e32 v24, v24, v154
	v_mul_f32_e32 v24, v24, v146
	s_and_saveexec_b64 s[2:3], s[44:45]
	s_cbranch_execz .LBB0_2903
	v_lshlrev_b32_e32 v147, 3, v143
	v_mov_b32_e32 v148, v246
	v_mov_b32_e32 v149, v247
	v_mov_b32_e32 v147, v24
	v_mov_b32_e32 v152, v24
	s_nop 0
	v_mov_b32_dpp v147, v147 quad_perm:[1,0,3,2] row_mask:0xf bank_mask:0xf
	v_cndmask_b32_e64 v153, v147, -v147, s[38:39]
	s_waitcnt vmcnt(0)
	v_pk_mul_f32 v[148:149], v[152:153], v[148:149]
	s_nop 0
	v_add_f32_e32 v24, v148, v149
.LBB0_2903:
	s_or_b64 exec, exec, s[2:3]
	v_mul_f32_e32 v25, v25, v155
	v_mul_f32_e32 v25, v25, v146
	s_and_saveexec_b64 s[2:3], s[44:45]
	s_cbranch_execz .LBB0_2905
	v_lshlrev_b32_e32 v147, 3, v143
	v_mov_b32_e32 v148, v248
	v_mov_b32_e32 v149, v249
	v_mov_b32_e32 v147, v25
	v_mov_b32_e32 v152, v25
	s_nop 0
	v_mov_b32_dpp v147, v147 quad_perm:[1,0,3,2] row_mask:0xf bank_mask:0xf
	v_cndmask_b32_e64 v153, v147, -v147, s[38:39]
	s_waitcnt vmcnt(0)
	v_pk_mul_f32 v[148:149], v[152:153], v[148:149]
	s_nop 0
	v_add_f32_e32 v25, v148, v149
.LBB0_2905:
	s_or_b64 exec, exec, s[2:3]
	v_mul_f32_e32 v26, v26, v151
	v_mul_f32_e32 v26, v26, v146
	s_and_saveexec_b64 s[2:3], s[44:45]
	s_cbranch_execz .LBB0_2907
	v_lshlrev_b32_e32 v148, 3, v143
	v_mov_b32_e32 v149, v1
	v_lshl_add_u64 v[148:149], s[12:13], 0, v[148:149]
	v_add_co_u32_e32 v148, vcc, 0x1000, v148
	v_mov_b32_e32 v147, v26
	s_nop 0
	v_addc_co_u32_e32 v149, vcc, 0, v149, vcc
	global_load_dwordx2 v[244:245], v[148:149], off offset:256
	global_load_dwordx2 v[246:247], v[148:149], off offset:512
	global_load_dwordx2 v[248:249], v[148:149], off offset:768
	global_load_dwordx2 v[148:149], v[148:149], off
	v_mov_b32_dpp v147, v147 quad_perm:[1,0,3,2] row_mask:0xf bank_mask:0xf
	v_cndmask_b32_e64 v153, v147, -v147, s[38:39]
	v_mov_b32_e32 v152, v26
	s_waitcnt vmcnt(0)
	v_pk_mul_f32 v[148:149], v[152:153], v[148:149]
	s_nop 0
	v_add_f32_e32 v26, v148, v149
.LBB0_2907:
	s_or_b64 exec, exec, s[2:3]
	v_mul_f32_e32 v27, v27, v150
	v_mul_f32_e32 v27, v27, v146
	s_and_saveexec_b64 s[2:3], s[44:45]
	s_cbranch_execz .LBB0_2909
	v_lshlrev_b32_e32 v148, 3, v143
	v_mov_b32_e32 v149, v1
	v_lshl_add_u64 v[148:149], s[12:13], 0, v[148:149]
	v_add_co_u32_e32 v148, vcc, 0x1000, v148
	v_mov_b32_e32 v147, v27
	s_nop 0
	v_addc_co_u32_e32 v149, vcc, 0, v149, vcc
	v_mov_b32_e32 v148, v244
	v_mov_b32_e32 v149, v245
	v_mov_b32_dpp v147, v147 quad_perm:[1,0,3,2] row_mask:0xf bank_mask:0xf
	v_cndmask_b32_e64 v153, v147, -v147, s[38:39]
	v_mov_b32_e32 v152, v27
	s_waitcnt vmcnt(0)
	v_pk_mul_f32 v[148:149], v[152:153], v[148:149]
	s_nop 0
	v_add_f32_e32 v27, v148, v149
.LBB0_2909:
	s_or_b64 exec, exec, s[2:3]
	v_mul_f32_e32 v28, v28, v145
	v_mul_f32_e32 v28, v28, v146
	s_and_saveexec_b64 s[2:3], s[44:45]
	s_cbranch_execz .LBB0_2911
	v_lshlrev_b32_e32 v148, 3, v143
	v_mov_b32_e32 v149, v1
	v_lshl_add_u64 v[148:149], s[12:13], 0, v[148:149]
	v_add_co_u32_e32 v148, vcc, 0x1000, v148
	v_mov_b32_e32 v147, v28
	s_nop 0
	v_addc_co_u32_e32 v149, vcc, 0, v149, vcc
	v_mov_b32_e32 v148, v246
	v_mov_b32_e32 v149, v247
	v_mov_b32_dpp v147, v147 quad_perm:[1,0,3,2] row_mask:0xf bank_mask:0xf
	v_cndmask_b32_e64 v153, v147, -v147, s[38:39]
	v_mov_b32_e32 v152, v28
	s_waitcnt vmcnt(0)
	v_pk_mul_f32 v[148:149], v[152:153], v[148:149]
	s_nop 0
	v_add_f32_e32 v28, v148, v149
.LBB0_2911:
	s_or_b64 exec, exec, s[2:3]
	v_mul_f32_e32 v29, v29, v144
	v_mul_f32_e32 v29, v29, v146
	s_and_saveexec_b64 s[2:3], s[44:45]
	s_cbranch_execz .LBB0_2913
	v_lshlrev_b32_e32 v148, 3, v143
	v_mov_b32_e32 v149, v1
	v_lshl_add_u64 v[148:149], s[12:13], 0, v[148:149]
	v_add_co_u32_e32 v148, vcc, 0x1000, v148
	v_mov_b32_e32 v147, v29
	s_nop 0
	v_addc_co_u32_e32 v149, vcc, 0, v149, vcc
	v_mov_b32_e32 v148, v248
	v_mov_b32_e32 v149, v249
	v_mov_b32_dpp v147, v147 quad_perm:[1,0,3,2] row_mask:0xf bank_mask:0xf
	v_cndmask_b32_e64 v153, v147, -v147, s[38:39]
	v_mov_b32_e32 v152, v29
	s_waitcnt vmcnt(0)
	v_pk_mul_f32 v[148:149], v[152:153], v[148:149]
	s_nop 0
	v_add_f32_e32 v29, v148, v149
.LBB0_2913:
	s_or_b64 exec, exec, s[2:3]
	v_mul_f32_e32 v30, v30, v141
	v_mul_f32_e32 v30, v30, v146
	s_and_saveexec_b64 s[2:3], s[44:45]
	s_cbranch_execz .LBB0_2915
	v_lshlrev_b32_e32 v148, 3, v143
	v_mov_b32_e32 v149, v1
	v_lshl_add_u64 v[148:149], s[12:13], 0, v[148:149]
	v_add_co_u32_e32 v148, vcc, 0x1000, v148
	v_mov_b32_e32 v147, v30
	s_nop 0
	v_addc_co_u32_e32 v149, vcc, 0, v149, vcc
	global_load_dwordx2 v[244:245], v[148:149], off offset:2304
	global_load_dwordx2 v[246:247], v[148:149], off offset:2560
	global_load_dwordx2 v[248:249], v[148:149], off offset:2816
	global_load_dwordx2 v[148:149], v[148:149], off offset:2048
	v_mov_b32_dpp v147, v147 quad_perm:[1,0,3,2] row_mask:0xf bank_mask:0xf
	v_cndmask_b32_e64 v153, v147, -v147, s[38:39]
	v_mov_b32_e32 v152, v30
	s_waitcnt vmcnt(0)
	v_pk_mul_f32 v[148:149], v[152:153], v[148:149]
	s_nop 0
	v_add_f32_e32 v30, v148, v149
; DEVI int crow(int r, int hi) { return (r & 3) + 8 * (r >> 2) + 4 * hi; }
; DEVI float xor1(float v) { return dppf<0xB1, 0xF>(v, v); }
;   DEVI void operator()(f32x16* acc, int mrow, int pn, int r32, int hi, char* slice) const {
;     ...
;       for (int j = 0; j < 4; ++j) {
;         const float g = gain[j * 32 + r32];
;         const int fi = (j & 1) * 16 + (r32 >> 1);
; #pragma unroll
;         for (int r = 0; r < 16; ++r) {
;           float v = acc[j][r] * rstd[r] * g;
;           if (latent) {
;             const int s = (mrow + crow(r, hi)) & (SEQ - 1);
;             const int idx = (j < 2) ? (s >> 6) : (s & 63);
;             const float2 cs = rope[idx * 32 + fi];
;             const float pr = xor1(v);
;             v = v * cs.x + (((r32 & 1) != DBG_BREAK) ? pr * cs.y : -pr * cs.y);
;           }
;           acc[j][r] = v;
.LBB0_2915:
	s_or_b64 exec, exec, s[2:3]
	v_mul_f32_e32 v31, v31, v140
	v_mul_f32_e32 v31, v31, v146
	s_and_saveexec_b64 s[2:3], s[44:45]
	s_cbranch_execz .LBB0_2917
	v_lshlrev_b32_e32 v148, 3, v143
	v_mov_b32_e32 v149, v1
	v_lshl_add_u64 v[148:149], s[12:13], 0, v[148:149]
	v_add_co_u32_e32 v148, vcc, 0x1000, v148
	v_mov_b32_e32 v147, v31
	s_nop 0
	v_addc_co_u32_e32 v149, vcc, 0, v149, vcc
	v_mov_b32_e32 v148, v244
	v_mov_b32_e32 v149, v245
	v_mov_b32_dpp v147, v147 quad_perm:[1,0,3,2] row_mask:0xf bank_mask:0xf
	v_cndmask_b32_e64 v153, v147, -v147, s[38:39]
	v_mov_b32_e32 v152, v31
	s_waitcnt vmcnt(0)
	v_pk_mul_f32 v[148:149], v[152:153], v[148:149]
	s_nop 0
	v_add_f32_e32 v31, v148, v149
.LBB0_2917:
	s_or_b64 exec, exec, s[2:3]
	v_mul_f32_e32 v32, v32, v139
	v_mul_f32_e32 v32, v32, v146
	s_and_saveexec_b64 s[2:3], s[44:45]
	s_cbranch_execz .LBB0_2919
	v_lshlrev_b32_e32 v148, 3, v143
	v_mov_b32_e32 v149, v1
	v_lshl_add_u64 v[148:149], s[12:13], 0, v[148:149]
	v_add_co_u32_e32 v148, vcc, 0x1000, v148
	v_mov_b32_e32 v147, v32
	s_nop 0
	v_addc_co_u32_e32 v149, vcc, 0, v149, vcc
	v_mov_b32_e32 v148, v246
	v_mov_b32_e32 v149, v247
	v_mov_b32_dpp v147, v147 quad_perm:[1,0,3,2] row_mask:0xf bank_mask:0xf
	v_cndmask_b32_e64 v153, v147, -v147, s[38:39]
	v_mov_b32_e32 v152, v32
	s_waitcnt vmcnt(0)
	v_pk_mul_f32 v[148:149], v[152:153], v[148:149]
	s_nop 0
	v_add_f32_e32 v32, v148, v149
.LBB0_2919:
	s_or_b64 exec, exec, s[2:3]
	v_mul_f32_e32 v33, v33, v138
	v_mul_f32_e32 v33, v33, v146
	s_and_saveexec_b64 s[2:3], s[44:45]
	s_cbranch_execz .LBB0_2921
	v_lshlrev_b32_e32 v146, 3, v143
	v_mov_b32_e32 v147, v1
	v_lshl_add_u64 v[146:147], s[12:13], 0, v[146:147]
	v_add_co_u32_e32 v146, vcc, 0x1000, v146
	v_mov_b32_e32 v143, v33
	s_nop 0
	v_addc_co_u32_e32 v147, vcc, 0, v147, vcc
	v_mov_b32_e32 v146, v248
	v_mov_b32_e32 v147, v249
	v_mov_b32_dpp v143, v143 quad_perm:[1,0,3,2] row_mask:0xf bank_mask:0xf
	v_cndmask_b32_e64 v149, v143, -v143, s[38:39]
	v_mov_b32_e32 v148, v33
	s_waitcnt vmcnt(0)
	v_pk_mul_f32 v[146:147], v[148:149], v[146:147]
	s_nop 0
	v_add_f32_e32 v33, v146, v147
.LBB0_2921:
	s_or_b64 exec, exec, s[2:3]
	global_load_dword v137, v[136:137], off offset:384
	v_mul_f32_e32 v2, v2, v199
	v_and_or_b32 v136, v142, s1, v171
	s_waitcnt vmcnt(0)
	v_mul_f32_e32 v2, v2, v137
	s_and_saveexec_b64 s[2:3], s[44:45]
	s_cbranch_execz .LBB0_2923
	v_lshlrev_b32_e32 v142, 3, v136
	global_load_dwordx2 v[244:245], v142, s[12:13] offset:256
	global_load_dwordx2 v[246:247], v142, s[12:13] offset:512
	global_load_dwordx2 v[248:249], v142, s[12:13] offset:768
	global_load_dwordx2 v[142:143], v142, s[12:13]
	v_mov_b32_e32 v146, v2
	s_nop 1
	v_mov_b32_dpp v146, v146 quad_perm:[1,0,3,2] row_mask:0xf bank_mask:0xf
	v_cndmask_b32_e64 v147, v146, -v146, s[38:39]
	v_mov_b32_e32 v146, v2
	s_waitcnt vmcnt(0)
	v_pk_mul_f32 v[142:143], v[146:147], v[142:143]
	s_nop 0
	v_add_f32_e32 v2, v142, v143
.LBB0_2923:
	s_or_b64 exec, exec, s[2:3]
	v_mul_f32_e32 v3, v3, v200
	v_mul_f32_e32 v3, v3, v137
	s_and_saveexec_b64 s[2:3], s[44:45]
	s_cbranch_execz .LBB0_2925
	v_lshlrev_b32_e32 v142, 3, v136
	v_mov_b32_e32 v142, v244
	v_mov_b32_e32 v143, v245
	v_mov_b32_e32 v146, v3
	s_nop 1
	v_mov_b32_dpp v146, v146 quad_perm:[1,0,3,2] row_mask:0xf bank_mask:0xf
	v_cndmask_b32_e64 v147, v146, -v146, s[38:39]
	v_mov_b32_e32 v146, v3
	s_waitcnt vmcnt(0)
	v_pk_mul_f32 v[142:143], v[146:147], v[142:143]
	s_nop 0
	v_add_f32_e32 v3, v142, v143
.LBB0_2925:
	s_or_b64 exec, exec, s[2:3]
	v_mul_f32_e32 v4, v4, v162
	v_mul_f32_e32 v4, v4, v137
	s_and_saveexec_b64 s[2:3], s[44:45]
	s_cbranch_execz .LBB0_2927
	v_lshlrev_b32_e32 v142, 3, v136
	v_mov_b32_e32 v142, v246
	v_mov_b32_e32 v143, v247
	v_mov_b32_e32 v146, v4
	s_nop 1
	v_mov_b32_dpp v146, v146 quad_perm:[1,0,3,2] row_mask:0xf bank_mask:0xf
	v_cndmask_b32_e64 v147, v146, -v146, s[38:39]
	v_mov_b32_e32 v146, v4
	s_waitcnt vmcnt(0)
	v_pk_mul_f32 v[142:143], v[146:147], v[142:143]
	s_nop 0
	v_add_f32_e32 v4, v142, v143
.LBB0_2927:
	s_or_b64 exec, exec, s[2:3]
	v_mul_f32_e32 v5, v5, v163
	v_mul_f32_e32 v5, v5, v137
	s_and_saveexec_b64 s[2:3], s[44:45]
	s_cbranch_execz .LBB0_2929
	v_lshlrev_b32_e32 v142, 3, v136
	v_mov_b32_e32 v142, v248
	v_mov_b32_e32 v143, v249
	v_mov_b32_e32 v146, v5
	s_nop 1
	v_mov_b32_dpp v146, v146 quad_perm:[1,0,3,2] row_mask:0xf bank_mask:0xf
	v_cndmask_b32_e64 v147, v146, -v146, s[38:39]
	v_mov_b32_e32 v146, v5
	s_waitcnt vmcnt(0)
	v_pk_mul_f32 v[142:143], v[146:147], v[142:143]
	s_nop 0
	v_add_f32_e32 v5, v142, v143
.LBB0_2929:
	s_or_b64 exec, exec, s[2:3]
	v_mul_f32_e32 v6, v6, v158
	v_mul_f32_e32 v6, v6, v137
	s_and_saveexec_b64 s[2:3], s[44:45]
	s_cbranch_execz .LBB0_2931
	v_lshlrev_b32_e32 v142, 3, v136
	global_load_dwordx2 v[244:245], v142, s[12:13] offset:2304
	global_load_dwordx2 v[246:247], v142, s[12:13] offset:2560
	global_load_dwordx2 v[248:249], v142, s[12:13] offset:2816
	global_load_dwordx2 v[142:143], v142, s[12:13] offset:2048
	v_mov_b32_e32 v146, v6
	s_nop 1
	v_mov_b32_dpp v146, v146 quad_perm:[1,0,3,2] row_mask:0xf bank_mask:0xf
	v_cndmask_b32_e64 v147, v146, -v146, s[38:39]
	v_mov_b32_e32 v146, v6
	s_waitcnt vmcnt(0)
	v_pk_mul_f32 v[142:143], v[146:147], v[142:143]
	s_nop 0
	v_add_f32_e32 v6, v142, v143
.LBB0_2931:
	s_or_b64 exec, exec, s[2:3]
	v_mul_f32_e32 v7, v7, v159
	v_mul_f32_e32 v7, v7, v137
	s_and_saveexec_b64 s[2:3], s[44:45]
	s_cbranch_execz .LBB0_2933
	v_lshlrev_b32_e32 v142, 3, v136
	v_mov_b32_e32 v142, v244
	v_mov_b32_e32 v143, v245
	v_mov_b32_e32 v146, v7
	s_nop 1
	v_mov_b32_dpp v146, v146 quad_perm:[1,0,3,2] row_mask:0xf bank_mask:0xf
	v_cndmask_b32_e64 v147, v146, -v146, s[38:39]
	v_mov_b32_e32 v146, v7
	s_waitcnt vmcnt(0)
	v_pk_mul_f32 v[142:143], v[146:147], v[142:143]
	s_nop 0
	v_add_f32_e32 v7, v142, v143
; DEVI int crow(int r, int hi) { return (r & 3) + 8 * (r >> 2) + 4 * hi; }
; DEVI float xor1(float v) { return dppf<0xB1, 0xF>(v, v); }
;   DEVI void operator()(f32x16* acc, int mrow, int pn, int r32, int hi, char* slice) const {
;     ...
;       for (int j = 0; j < 4; ++j) {
;         const float g = gain[j * 32 + r32];
;         const int fi = (j & 1) * 16 + (r32 >> 1);
; #pragma unroll
;         for (int r = 0; r < 16; ++r) {
;           float v = acc[j][r] * rstd[r] * g;
;           if (latent) {
;             const int s = (mrow + crow(r, hi)) & (SEQ - 1);
;             const int idx = (j < 2) ? (s >> 6) : (s & 63);
;             const float2 cs = rope[idx * 32 + fi];
;             const float pr = xor1(v);
;             v = v * cs.x + (((r32 & 1) != DBG_BREAK) ? pr * cs.y : -pr * cs.y);
;           }
;           acc[j][r] = v;
.LBB0_2933:
	s_or_b64 exec, exec, s[2:3]
	v_mul_f32_e32 v8, v8, v154
	v_mul_f32_e32 v8, v8, v137
	s_and_saveexec_b64 s[2:3], s[44:45]
	s_cbranch_execz .LBB0_2935
	v_lshlrev_b32_e32 v142, 3, v136
	v_mov_b32_e32 v142, v246
	v_mov_b32_e32 v143, v247
	v_mov_b32_e32 v146, v8
	s_nop 1
	v_mov_b32_dpp v146, v146 quad_perm:[1,0,3,2] row_mask:0xf bank_mask:0xf
	v_cndmask_b32_e64 v147, v146, -v146, s[38:39]
	v_mov_b32_e32 v146, v8
	s_waitcnt vmcnt(0)
	v_pk_mul_f32 v[142:143], v[146:147], v[142:143]
	s_nop 0
	v_add_f32_e32 v8, v142, v143
.LBB0_2935:
	s_or_b64 exec, exec, s[2:3]
	v_mul_f32_e32 v9, v9, v155
	v_mul_f32_e32 v9, v9, v137
	s_and_saveexec_b64 s[2:3], s[44:45]
	s_cbranch_execz .LBB0_2937
	v_lshlrev_b32_e32 v142, 3, v136
	v_mov_b32_e32 v142, v248
	v_mov_b32_e32 v143, v249
	v_mov_b32_e32 v146, v9
	s_nop 1
	v_mov_b32_dpp v146, v146 quad_perm:[1,0,3,2] row_mask:0xf bank_mask:0xf
	v_cndmask_b32_e64 v147, v146, -v146, s[38:39]
	v_mov_b32_e32 v146, v9
	s_waitcnt vmcnt(0)
	v_pk_mul_f32 v[142:143], v[146:147], v[142:143]
	s_nop 0
	v_add_f32_e32 v9, v142, v143
.LBB0_2937:
	s_or_b64 exec, exec, s[2:3]
	v_mul_f32_e32 v10, v10, v151
	v_mul_f32_e32 v10, v10, v137
	s_and_saveexec_b64 s[2:3], s[44:45]
	s_cbranch_execz .LBB0_2939
	v_lshlrev_b32_e32 v142, 3, v136
	v_mov_b32_e32 v143, v1
	v_lshl_add_u64 v[142:143], s[12:13], 0, v[142:143]
	v_add_co_u32_e32 v142, vcc, 0x1000, v142
	v_mov_b32_e32 v146, v10
	s_nop 0
	v_addc_co_u32_e32 v143, vcc, 0, v143, vcc
	global_load_dwordx2 v[244:245], v[142:143], off offset:256
	global_load_dwordx2 v[246:247], v[142:143], off offset:512
	global_load_dwordx2 v[248:249], v[142:143], off offset:768
	global_load_dwordx2 v[142:143], v[142:143], off
	v_mov_b32_dpp v146, v146 quad_perm:[1,0,3,2] row_mask:0xf bank_mask:0xf
	v_cndmask_b32_e64 v147, v146, -v146, s[38:39]
	v_mov_b32_e32 v146, v10
	s_waitcnt vmcnt(0)
	v_pk_mul_f32 v[142:143], v[146:147], v[142:143]
	s_nop 0
	v_add_f32_e32 v10, v142, v143
.LBB0_2939:
	s_or_b64 exec, exec, s[2:3]
	v_mul_f32_e32 v11, v11, v150
	v_mul_f32_e32 v11, v11, v137
	s_and_saveexec_b64 s[2:3], s[44:45]
	s_cbranch_execz .LBB0_2941
	v_lshlrev_b32_e32 v142, 3, v136
	v_mov_b32_e32 v143, v1
	v_lshl_add_u64 v[142:143], s[12:13], 0, v[142:143]
	v_add_co_u32_e32 v142, vcc, 0x1000, v142
	v_mov_b32_e32 v146, v11
	s_nop 0
	v_addc_co_u32_e32 v143, vcc, 0, v143, vcc
	v_mov_b32_e32 v142, v244
	v_mov_b32_e32 v143, v245
	v_mov_b32_dpp v146, v146 quad_perm:[1,0,3,2] row_mask:0xf bank_mask:0xf
	v_cndmask_b32_e64 v147, v146, -v146, s[38:39]
	v_mov_b32_e32 v146, v11
	s_waitcnt vmcnt(0)
	v_pk_mul_f32 v[142:143], v[146:147], v[142:143]
	s_nop 0
	v_add_f32_e32 v11, v142, v143
.LBB0_2941:
	s_or_b64 exec, exec, s[2:3]
	v_mul_f32_e32 v12, v12, v145
	v_mul_f32_e32 v12, v12, v137
	s_and_saveexec_b64 s[2:3], s[44:45]
	s_cbranch_execz .LBB0_2943
	v_lshlrev_b32_e32 v142, 3, v136
	v_mov_b32_e32 v143, v1
	v_lshl_add_u64 v[142:143], s[12:13], 0, v[142:143]
	v_add_co_u32_e32 v142, vcc, 0x1000, v142
	v_mov_b32_e32 v145, v12
	s_nop 0
	v_addc_co_u32_e32 v143, vcc, 0, v143, vcc
	v_mov_b32_e32 v142, v246
	v_mov_b32_e32 v143, v247
	v_mov_b32_dpp v145, v145 quad_perm:[1,0,3,2] row_mask:0xf bank_mask:0xf
	v_cndmask_b32_e64 v147, v145, -v145, s[38:39]
	v_mov_b32_e32 v146, v12
	s_waitcnt vmcnt(0)
	v_pk_mul_f32 v[142:143], v[146:147], v[142:143]
	s_nop 0
	v_add_f32_e32 v12, v142, v143
.LBB0_2943:
	s_or_b64 exec, exec, s[2:3]
	v_mul_f32_e32 v13, v13, v144
	v_mul_f32_e32 v13, v13, v137
	s_and_saveexec_b64 s[2:3], s[44:45]
	s_cbranch_execz .LBB0_2945
	v_lshlrev_b32_e32 v142, 3, v136
	v_mov_b32_e32 v143, v1
	v_lshl_add_u64 v[142:143], s[12:13], 0, v[142:143]
	v_add_co_u32_e32 v142, vcc, 0x1000, v142
	v_mov_b32_e32 v144, v13
	s_nop 0
	v_addc_co_u32_e32 v143, vcc, 0, v143, vcc
	v_mov_b32_e32 v142, v248
	v_mov_b32_e32 v143, v249
	v_mov_b32_dpp v144, v144 quad_perm:[1,0,3,2] row_mask:0xf bank_mask:0xf
	v_cndmask_b32_e64 v145, v144, -v144, s[38:39]
	v_mov_b32_e32 v144, v13
	s_waitcnt vmcnt(0)
	v_pk_mul_f32 v[142:143], v[144:145], v[142:143]
	s_nop 0
	v_add_f32_e32 v13, v142, v143
.LBB0_2945:
	s_or_b64 exec, exec, s[2:3]
	v_mul_f32_e32 v14, v14, v141
	v_mul_f32_e32 v14, v14, v137
	s_and_saveexec_b64 s[2:3], s[44:45]
	s_cbranch_execz .LBB0_2947
	v_lshlrev_b32_e32 v142, 3, v136
	v_mov_b32_e32 v143, v1
	v_lshl_add_u64 v[142:143], s[12:13], 0, v[142:143]
	v_add_co_u32_e32 v142, vcc, 0x1000, v142
	v_mov_b32_e32 v141, v14
	s_nop 0
	v_addc_co_u32_e32 v143, vcc, 0, v143, vcc
	global_load_dwordx2 v[244:245], v[142:143], off offset:2304
	global_load_dwordx2 v[246:247], v[142:143], off offset:2560
	global_load_dwordx2 v[248:249], v[142:143], off offset:2816
	global_load_dwordx2 v[142:143], v[142:143], off offset:2048
	v_mov_b32_dpp v141, v141 quad_perm:[1,0,3,2] row_mask:0xf bank_mask:0xf
	v_cndmask_b32_e64 v145, v141, -v141, s[38:39]
	v_mov_b32_e32 v144, v14
	s_waitcnt vmcnt(0)
	v_pk_mul_f32 v[142:143], v[144:145], v[142:143]
	s_nop 0
	v_add_f32_e32 v14, v142, v143
.LBB0_2947:
	s_or_b64 exec, exec, s[2:3]
	v_mul_f32_e32 v15, v15, v140
	v_mul_f32_e32 v15, v15, v137
	s_and_saveexec_b64 s[2:3], s[44:45]
	s_cbranch_execz .LBB0_2949
	v_lshlrev_b32_e32 v140, 3, v136
	v_mov_b32_e32 v141, v1
	v_lshl_add_u64 v[140:141], s[12:13], 0, v[140:141]
	v_add_co_u32_e32 v140, vcc, 0x1000, v140
	v_mov_b32_e32 v142, v15
	s_nop 0
	v_addc_co_u32_e32 v141, vcc, 0, v141, vcc
	v_mov_b32_e32 v140, v244
	v_mov_b32_e32 v141, v245
	v_mov_b32_dpp v142, v142 quad_perm:[1,0,3,2] row_mask:0xf bank_mask:0xf
	v_cndmask_b32_e64 v143, v142, -v142, s[38:39]
	v_mov_b32_e32 v142, v15
	s_waitcnt vmcnt(0)
	v_pk_mul_f32 v[140:141], v[142:143], v[140:141]
	s_nop 0
	v_add_f32_e32 v15, v140, v141
.LBB0_2949:
	s_or_b64 exec, exec, s[2:3]
	v_mul_f32_e32 v16, v16, v139
	v_mul_f32_e32 v16, v16, v137
	s_and_saveexec_b64 s[2:3], s[44:45]
	s_cbranch_execz .LBB0_2951
	v_lshlrev_b32_e32 v140, 3, v136
	v_mov_b32_e32 v141, v1
	v_lshl_add_u64 v[140:141], s[12:13], 0, v[140:141]
	v_add_co_u32_e32 v140, vcc, 0x1000, v140
	v_mov_b32_e32 v139, v16
	s_nop 0
	v_addc_co_u32_e32 v141, vcc, 0, v141, vcc
	v_mov_b32_e32 v140, v246
	v_mov_b32_e32 v141, v247
	v_mov_b32_dpp v139, v139 quad_perm:[1,0,3,2] row_mask:0xf bank_mask:0xf
	v_cndmask_b32_e64 v143, v139, -v139, s[38:39]
	v_mov_b32_e32 v142, v16
	s_waitcnt vmcnt(0)
	v_pk_mul_f32 v[140:141], v[142:143], v[140:141]
	s_nop 0
	v_add_f32_e32 v16, v140, v141
.LBB0_2951:
	s_or_b64 exec, exec, s[2:3]
	v_mul_f32_e32 v17, v17, v138
	v_mul_f32_e32 v17, v17, v137
	s_and_saveexec_b64 s[2:3], s[44:45]
	s_cbranch_execz .LBB0_2953
	v_lshlrev_b32_e32 v136, 3, v136
	v_mov_b32_e32 v137, v1
	v_lshl_add_u64 v[136:137], s[12:13], 0, v[136:137]
	v_add_co_u32_e32 v136, vcc, 0x1000, v136
	v_mov_b32_e32 v138, v17
	s_nop 0
	v_addc_co_u32_e32 v137, vcc, 0, v137, vcc
	v_mov_b32_e32 v136, v248
	v_mov_b32_e32 v137, v249
	v_mov_b32_dpp v138, v138 quad_perm:[1,0,3,2] row_mask:0xf bank_mask:0xf
	v_cndmask_b32_e64 v139, v138, -v138, s[38:39]
	v_mov_b32_e32 v138, v17
	s_waitcnt vmcnt(0)
	v_pk_mul_f32 v[136:137], v[138:139], v[136:137]
	s_nop 0
	v_add_f32_e32 v17, v136, v137
